# mixer-A attention: added a specialised bounded-logit (skipmax) tile loop, 3-stage software pipeline PV(n-1)|softmax(n)|QK(n+1), 4 key tiles per trip with static LDS offsets, QK accumulates from inline
# speedup vs baseline: 1.0513x; 1.0423x over previous
.LBB0_176:
	s_and_b64 vcc, exec, s[0:1]
	s_cbranch_vccz .LBB0_196
	v_mbcnt_lo_u32_b32 v204, -1, 0
	v_mbcnt_hi_u32_b32 v204, -1, v204
	v_readlane_b32 s4, v254, 60
	v_and_b32_e32 v205, 63, v204
	v_readlane_b32 s0, v253, 39
	v_or_b32_e32 v0, s4, v205
	v_lshlrev_b32_e32 v0, 2, v0
	global_load_dword v36, v0, s[54:55]
	global_load_dword v37, v0, s[56:57]
	v_readlane_b32 s1, v253, 40
	s_and_b64 s[0:1], s[0:1], exec
	v_xor_b32_e32 v0, 32, v221
	s_cselect_b32 s0, s21, s43
	v_cmp_lt_i32_e32 vcc, v0, v222
	v_bfe_u32 v206, v204, 5, 1
	s_cselect_b32 s22, s9, s20
	s_lshl_b32 s0, s0, 8
	v_readlane_b32 s1, v254, 36
	v_readlane_b32 s18, v253, 15
	v_cndmask_b32_e32 v38, v221, v0, vcc
	v_and_b32_e32 v4, 31, v204
	v_lshlrev_b32_e32 v0, 6, v206
	s_or_b32 s0, s0, s1
	v_readlane_b32 s19, v253, 16
	v_mov_b32_e32 v213, v1
	s_lshl_b32 s45, s30, 11
	v_lshlrev_b32_e32 v212, 7, v4
	v_lshl_add_u64 v[6:7], s[18:19], 0, v[0:1]
	v_or_b32_e32 v4, s0, v4
	s_lshl_b32 s0, s0, 1
	v_cmp_lt_i32_e32 vcc, v217, v222
	v_mov_b64_e32 v[2:3], s[74:75]
	v_lshl_add_u64 v[8:9], v[6:7], 0, v[212:213]
	s_add_u32 s0, s18, s0
	v_add_u32_e32 v10, s45, v4
	s_movk_i32 s5, 0x14c0
	v_cndmask_b32_e32 v39, v221, v217, vcc
	v_cmp_lt_i32_e32 vcc, v225, v222
	global_load_dwordx4 v[18:21], v[8:9], off
	global_load_dwordx4 v[22:25], v[8:9], off offset:16
	global_load_dwordx4 v[26:29], v[8:9], off offset:32
	global_load_dwordx4 v[42:45], v[8:9], off offset:48
	v_or_b32_e32 v4, 32, v4
	s_addc_u32 s1, s19, 0
	v_mad_u64_u32 v[8:9], s[18:19], v10, s5, v[2:3]
	s_lshl_b32 s28, s22, 7
	v_cndmask_b32_e32 v40, v221, v225, vcc
	v_cmp_lt_i32_e32 vcc, v226, v222
	v_mov_b32_e32 v33, v1
	v_lshlrev_b32_e32 v32, 4, v206
	s_lshl_b32 s18, s4, 2
	v_add_u32_e32 v10, s45, v4
	v_lshl_add_u64 v[8:9], v[8:9], 0, s[28:29]
	v_cndmask_b32_e32 v41, v221, v226, vcc
	v_cmp_lt_i32_e32 vcc, v227, v222
	v_lshlrev_b32_e32 v4, 7, v4
	v_and_or_b32 v156, v204, 32, s18
	v_mad_u64_u32 v[2:3], s[18:19], v10, s5, v[2:3]
	v_lshl_add_u64 v[8:9], v[8:9], 0, v[32:33]
	s_mov_b32 s4, 0x4400000
	v_cndmask_b32_e32 v46, v221, v227, vcc
	v_mov_b32_e32 v5, v1
	v_and_b32_e32 v4, 0x1f80, v4
	s_mov_b64 s[18:19], 0x4400200
	v_add_co_u32_e32 v16, vcc, s4, v8
	v_lshl_add_u64 v[30:31], v[6:7], 0, v[4:5]
	v_lshl_add_u64 v[14:15], v[8:9], 0, s[18:19]
	v_addc_co_u32_e32 v17, vcc, 0, v9, vcc
	v_lshl_add_u64 v[34:35], v[2:3], 0, s[28:29]
	global_load_dwordx4 v[10:13], v156, s[54:55] offset:144
	global_load_dwordx4 v[6:9], v[30:31], off offset:32
	global_load_dwordx4 v[2:5], v[30:31], off offset:48
	global_load_dwordx4 v[90:93], v[16:17], off offset:512
	global_load_dwordx4 v[86:89], v[14:15], off offset:96
	global_load_dwordx4 v[82:85], v[14:15], off offset:32
	global_load_dwordx4 v[94:97], v[14:15], off offset:64
	s_nop 0
	global_load_dwordx4 v[14:17], v156, s[54:55] offset:208
	v_lshl_add_u64 v[32:33], v[34:35], 0, v[32:33]
	v_lshl_add_u64 v[34:35], v[32:33], 0, s[18:19]
	v_add_co_u32_e32 v32, vcc, s4, v32
	v_lshlrev_b32_e32 v46, 2, v46
	s_nop 0
	v_addc_co_u32_e32 v33, vcc, 0, v33, vcc
	global_load_dwordx4 v[50:53], v[34:35], off offset:32
	global_load_dwordx4 v[74:77], v[34:35], off offset:64
	global_load_dwordx4 v[70:73], v[32:33], off offset:512
	global_load_dwordx4 v[78:81], v[34:35], off offset:96
	v_lshlrev_b32_e32 v33, 2, v38
	v_lshlrev_b32_e32 v34, 2, v39
	v_lshlrev_b32_e32 v38, 2, v40
	v_cmp_lt_i32_e32 vcc, v228, v222
	s_mov_b32 s4, 0x3e38aa3b
	s_add_u32 s18, s74, s31
	v_cndmask_b32_e32 v32, v221, v228, vcc
	s_waitcnt vmcnt(17)
	v_and_b32_e32 v35, 0x7fffffff, v36
	ds_bpermute_b32 v35, v33, v35
	s_waitcnt vmcnt(16)
	v_and_b32_e32 v39, 0x7fffffff, v37
	ds_bpermute_b32 v33, v33, v39
	v_max_f32_e64 v36, |v36|, |v36|
	v_max_f32_e64 v37, |v37|, |v37|
	s_waitcnt lgkmcnt(1)
	v_max_f32_e32 v35, v35, v35
	v_max_f32_e32 v35, v36, v35
	s_waitcnt lgkmcnt(0)
	v_max_f32_e32 v33, v33, v33
	ds_bpermute_b32 v36, v34, v35
	v_max_f32_e32 v33, v37, v33
	ds_bpermute_b32 v34, v34, v33
	v_lshlrev_b32_e32 v37, 2, v41
	v_lshlrev_b32_e32 v32, 2, v32
	s_waitcnt lgkmcnt(1)
	v_max_f32_e32 v36, v36, v36
	v_max_f32_e32 v35, v35, v36
	s_waitcnt lgkmcnt(0)
	v_max_f32_e32 v34, v34, v34
	ds_bpermute_b32 v36, v38, v35
	v_max_f32_e32 v33, v33, v34
	ds_bpermute_b32 v34, v38, v33
	global_load_dwordx4 v[38:41], v156, s[54:55] offset:192
	s_addc_u32 s19, s75, 0
	s_waitcnt lgkmcnt(1)
	v_max_f32_e32 v36, v36, v36
	v_max_f32_e32 v35, v35, v36
	s_waitcnt lgkmcnt(0)
	v_max_f32_e32 v34, v34, v34
	ds_bpermute_b32 v36, v37, v35
	v_max_f32_e32 v33, v33, v34
	ds_bpermute_b32 v34, v37, v33
	s_waitcnt vmcnt(16)
	v_mov_b32_e32 v108, v19
	v_mov_b32_e32 v109, v20
	s_waitcnt lgkmcnt(1)
	v_max_f32_e32 v36, v36, v36
	v_max_f32_e32 v35, v35, v36
	s_waitcnt lgkmcnt(0)
	v_max_f32_e32 v34, v34, v34
	ds_bpermute_b32 v36, v46, v35
	v_max_f32_e32 v33, v33, v34
	ds_bpermute_b32 v34, v46, v33
	global_load_dwordx4 v[46:49], v156, s[54:55] offset:128
	s_waitcnt vmcnt(14)
	v_mov_b32_e32 v122, v43
	s_waitcnt lgkmcnt(1)
	v_max_f32_e32 v36, v36, v36
	v_max_f32_e32 v54, v35, v36
	s_waitcnt lgkmcnt(0)
	v_max_f32_e32 v34, v34, v34
	ds_bpermute_b32 v35, v32, v54
	v_max_f32_e32 v55, v33, v34
	ds_bpermute_b32 v56, v32, v55
	v_mov_b32_e32 v123, v44
	v_mov_b32_e32 v132, v42
	s_waitcnt lgkmcnt(1)
	v_max_f32_e32 v57, v35, v35
	v_max_f32_e32 v54, v54, v57
	s_waitcnt lgkmcnt(0)
	v_max_f32_e32 v56, v56, v56
	v_max_f32_e32 v55, v55, v56
	v_mul_f32_e32 v54, 0x41000000, v54
	v_mul_f32_e32 v54, v55, v54
	global_load_dwordx4 v[34:37], v[30:31], off
	s_nop 0
	global_load_dwordx4 v[30:33], v[30:31], off offset:16
	v_mul_f32_e32 v54, 0x3fb8aa3b, v54
	v_mul_f32_e32 v207, 0x3f866666, v54
	global_load_dwordx4 v[62:65], v156, s[54:55] offset:80
	global_load_dwordx4 v[66:69], v156, s[54:55] offset:16
	v_mov_b32_e32 v194, v42
	v_mov_b32_e32 v195, v44
	v_mov_b32_e32 v44, v43
	v_mov_b32_e32 v160, v18
	v_mov_b32_e32 v154, v18
	s_waitcnt vmcnt(13)
	v_lshlrev_b32_e32 v128, 16, v89
	v_and_b32_e32 v55, 0xffff0000, v89
	s_waitcnt vmcnt(11)
	v_and_b32_e32 v129, 0xffff0000, v97
	v_and_b32_e32 v54, 16, v97
	v_mov_b32_e32 v131, v55
	v_pk_mov_b32 v[186:187], v[54:55], v[128:129] op_sel:[1,0]
	global_load_dwordx4 v[54:57], v0, s[0:1] offset:32
	global_load_dwordx4 v[58:61], v0, s[0:1] offset:48
	s_waitcnt vmcnt(12)
	v_mov_b32_e32 v100, v16
	v_mov_b32_e32 v101, v13
	v_mov_b32_e32 v13, v17
	s_waitcnt vmcnt(10)
	v_and_b32_e32 v105, 0xffff0000, v77
	s_waitcnt vmcnt(8)
	v_lshlrev_b32_e32 v104, 16, v81
	v_and_b32_e32 v17, 0xffff0000, v81
	v_and_b32_e32 v16, 16, v77
	v_mov_b32_e32 v107, v17
	v_pk_mov_b32 v[134:135], v[16:17], v[104:105] op_sel:[1,0]
	v_lshlrev_b32_e32 v126, 16, v88
	v_and_b32_e32 v127, 0xffff0000, v96
	v_and_b32_e32 v17, 0xffff0000, v88
	v_and_b32_e32 v16, 16, v96
	v_lshlrev_b32_e32 v130, 16, v97
	v_lshlrev_b32_e32 v124, 16, v96
	v_mov_b32_e32 v125, v17
	v_pk_mov_b32 v[196:197], v[16:17], v[126:127] op_sel:[1,0]
	v_mov_b32_e32 v96, v6
	v_mov_b32_e32 v97, v8
	v_mov_b32_e32 v8, v7
	v_lshlrev_b32_e32 v138, 16, v87
	v_and_b32_e32 v139, 0xffff0000, v95
	v_and_b32_e32 v7, 0xffff0000, v87
	v_and_b32_e32 v6, 16, v95
	v_lshlrev_b32_e32 v142, 16, v86
	v_and_b32_e32 v143, 0xffff0000, v94
	v_and_b32_e32 v17, 0xffff0000, v86
	v_and_b32_e32 v16, 16, v94
	v_lshlrev_b32_e32 v106, 16, v77
	v_lshlrev_b32_e32 v116, 16, v76
	v_and_b32_e32 v117, 0xffff0000, v76
	v_lshlrev_b32_e32 v114, 16, v80
	v_and_b32_e32 v115, 0xffff0000, v80
	v_mov_b32_e32 v137, v7
	v_pk_mov_b32 v[200:201], v[6:7], v[138:139] op_sel:[1,0]
	v_lshlrev_b32_e32 v120, 16, v75
	v_and_b32_e32 v121, 0xffff0000, v75
	v_lshlrev_b32_e32 v118, 16, v79
	v_and_b32_e32 v119, 0xffff0000, v79
	v_mov_b32_e32 v141, v17
	v_pk_mov_b32 v[202:203], v[16:17], v[142:143] op_sel:[1,0]
	v_mov_b32_e32 v155, v20
	v_mov_b32_e32 v20, v19
	v_lshlrev_b32_e32 v42, 16, v74
	v_and_b32_e32 v43, 0xffff0000, v74
	v_and_b32_e32 v189, 0xffff0000, v91
	v_lshlrev_b32_e32 v190, 16, v91
	v_and_b32_e32 v91, 0xffff0000, v90
	v_lshlrev_b32_e32 v192, 16, v90
	v_and_b32_e32 v193, 0xffff0000, v82
	v_mov_b32_e32 v112, v27
	v_mov_b32_e32 v113, v28
	v_mov_b32_e32 v148, v26
	v_lshlrev_b32_e32 v136, 16, v95
	v_lshlrev_b32_e32 v140, 16, v94
	v_mov_b32_e32 v182, v26
	v_mov_b32_e32 v183, v28
	v_mov_b32_e32 v28, v27
	v_lshlrev_b32_e32 v94, 16, v73
	v_and_b32_e32 v95, 0xffff0000, v73
	v_lshlrev_b32_e32 v188, 16, v83
	v_and_b32_e32 v191, 0xffff0000, v83
	v_lshlrev_b32_e32 v90, 16, v82
	v_and_b32_e32 v73, 0xffff0000, v71
	s_waitcnt vmcnt(4)
	v_mov_b32_e32 v6, v30
	v_mov_b32_e32 v7, v32
	v_mov_b32_e32 v32, v31
	v_lshlrev_b32_e32 v30, 16, v78
	v_and_b32_e32 v31, 0xffff0000, v78
	global_load_dwordx4 v[86:89], v156, s[54:55]
	global_load_dwordx4 v[78:81], v156, s[54:55] offset:64
	global_load_dwordx4 v[74:77], v0, s[0:1]
	global_load_dwordx4 v[16:19], v0, s[0:1] offset:16
	v_mul_f32_e32 v0, v91, v91
	v_lshlrev_b32_e32 v82, 16, v70
	v_and_b32_e32 v83, 0xffff0000, v70
	v_and_b32_e32 v157, 0xffff0000, v93
	v_lshlrev_b32_e32 v158, 16, v93
	v_and_b32_e32 v177, 0xffff0000, v92
	v_lshlrev_b32_e32 v92, 16, v92
	v_and_b32_e32 v93, 0xffff0000, v84
	v_and_b32_e32 v159, 0xffff0000, v85
	s_waitcnt vmcnt(4)
	v_mov_b32_e32 v168, v59
	v_mov_b32_e32 v169, v60
	v_mov_b32_e32 v174, v58
	v_mov_b32_e32 v26, v58
	v_mov_b32_e32 v27, v60
	v_mov_b32_e32 v60, v59
	v_lshlrev_b32_e32 v58, 16, v72
	v_and_b32_e32 v59, 0xffff0000, v72
	v_lshlrev_b32_e32 v72, 16, v71
	v_pk_fma_f32 v[70:71], v[192:193], v[192:193], v[0:1] op_sel_hi:[1,1,0]
	v_mul_f32_e32 v0, v189, v189
	v_pk_fma_f32 v[70:71], v[190:191], v[190:191], v[70:71]
	v_lshlrev_b32_e32 v176, 16, v84
	v_pk_add_f32 v[70:71], v[0:1], v[70:71] op_sel_hi:[0,1]
	v_pk_fma_f32 v[70:71], v[92:93], v[92:93], v[70:71]
	v_mul_f32_e32 v0, v177, v177
	v_pk_add_f32 v[70:71], v[0:1], v[70:71] op_sel_hi:[0,1]
	v_pk_fma_f32 v[70:71], v[158:159], v[158:159], v[70:71]
	v_mul_f32_e32 v0, v157, v157
	v_pk_add_f32 v[70:71], v[0:1], v[70:71] op_sel_hi:[0,1]
	v_pk_fma_f32 v[70:71], v[90:91], v[90:91], v[70:71]
	v_mul_f32_e32 v0, v193, v193
	v_pk_add_f32 v[70:71], v[0:1], v[70:71] op_sel_hi:[0,1]
	v_pk_fma_f32 v[70:71], v[188:189], v[188:189], v[70:71]
	v_mul_f32_e32 v0, v191, v191
	v_pk_add_f32 v[70:71], v[0:1], v[70:71] op_sel_hi:[0,1]
	v_pk_fma_f32 v[70:71], v[176:177], v[176:177], v[70:71]
	v_mul_f32_e32 v0, v93, v93
	v_lshlrev_b32_e32 v156, 16, v85
	v_pk_add_f32 v[70:71], v[0:1], v[70:71] op_sel_hi:[0,1]
	v_pk_fma_f32 v[70:71], v[156:157], v[156:157], v[70:71]
	v_mul_f32_e32 v0, v159, v159
	v_pk_add_f32 v[70:71], v[0:1], v[70:71] op_sel_hi:[0,1]
	v_pk_fma_f32 v[70:71], v[140:141], v[140:141], v[70:71]
	v_mul_f32_e32 v0, v143, v143
	v_pk_add_f32 v[70:71], v[0:1], v[70:71] op_sel_hi:[0,1]
	v_pk_fma_f32 v[70:71], v[136:137], v[136:137], v[70:71]
	v_mul_f32_e32 v0, v139, v139
	v_pk_add_f32 v[70:71], v[0:1], v[70:71] op_sel_hi:[0,1]
	v_pk_fma_f32 v[70:71], v[124:125], v[124:125], v[70:71]
	v_mul_f32_e32 v0, v127, v127
	v_pk_add_f32 v[70:71], v[0:1], v[70:71] op_sel_hi:[0,1]
	v_pk_fma_f32 v[70:71], v[130:131], v[130:131], v[70:71]
	v_mul_f32_e32 v0, v129, v129
	v_pk_add_f32 v[70:71], v[0:1], v[70:71] op_sel_hi:[0,1]
	v_mul_f32_e32 v0, v203, v203
	v_pk_add_f32 v[70:71], v[0:1], v[70:71] op_sel_hi:[0,1]
	v_pk_fma_f32 v[70:71], v[202:203], v[202:203], v[70:71]
	v_mul_f32_e32 v0, v201, v201
	v_pk_add_f32 v[202:203], v[0:1], v[70:71] op_sel_hi:[0,1]
	v_mov_b32_e32 v110, v23
	v_mov_b32_e32 v111, v24
	v_mov_b32_e32 v144, v22
	v_mov_b32_e32 v166, v22
	v_mov_b32_e32 v167, v24
	v_mov_b32_e32 v24, v23
	v_mov_b32_e32 v22, v34
	v_mov_b32_e32 v23, v36
	v_mov_b32_e32 v36, v35
	v_lshlrev_b32_e32 v34, 16, v53
	v_and_b32_e32 v35, 0xffff0000, v53
	v_lshlrev_b32_e32 v70, 16, v52
	v_and_b32_e32 v71, 0xffff0000, v52
	v_pk_fma_f32 v[52:53], v[200:201], v[200:201], v[202:203]
	v_mul_f32_e32 v0, v197, v197
	v_pk_add_f32 v[200:201], v[0:1], v[52:53] op_sel_hi:[0,1]
	v_pk_fma_f32 v[196:197], v[196:197], v[196:197], v[200:201]
	v_mul_f32_e32 v0, v187, v187
	v_pk_add_f32 v[200:201], v[0:1], v[196:197] op_sel_hi:[0,1]
	v_mul_f32_e32 v0, v83, v83
	v_lshlrev_b32_e32 v196, 16, v51
	v_and_b32_e32 v197, 0xffff0000, v51
	v_pk_fma_f32 v[200:201], v[186:187], v[186:187], v[200:201]
	v_lshlrev_b32_e32 v186, 16, v50
	v_and_b32_e32 v187, 0xffff0000, v50
	v_pk_fma_f32 v[50:51], v[82:83], v[82:83], v[0:1] op_sel_hi:[1,1,0]
	v_mul_f32_e32 v0, v73, v73
	v_pk_fma_f32 v[50:51], v[72:73], v[72:73], v[50:51]
	v_mov_b32_e32 v203, v200
	v_pk_add_f32 v[50:51], v[0:1], v[50:51] op_sel_hi:[0,1]
	v_pk_fma_f32 v[50:51], v[58:59], v[58:59], v[50:51]
	v_mul_f32_e32 v0, v59, v59
	v_pk_add_f32 v[50:51], v[0:1], v[50:51] op_sel_hi:[0,1]
	v_pk_fma_f32 v[50:51], v[94:95], v[94:95], v[50:51]
	v_mul_f32_e32 v0, v95, v95
	v_pk_add_f32 v[50:51], v[0:1], v[50:51] op_sel_hi:[0,1]
	v_pk_fma_f32 v[50:51], v[186:187], v[186:187], v[50:51]
	v_mul_f32_e32 v0, v187, v187
	v_pk_add_f32 v[50:51], v[0:1], v[50:51] op_sel_hi:[0,1]
	v_pk_fma_f32 v[50:51], v[196:197], v[196:197], v[50:51]
	v_mul_f32_e32 v0, v197, v197
	v_pk_add_f32 v[50:51], v[0:1], v[50:51] op_sel_hi:[0,1]
	v_pk_fma_f32 v[50:51], v[70:71], v[70:71], v[50:51]
	v_mul_f32_e32 v0, v71, v71
	v_pk_add_f32 v[50:51], v[0:1], v[50:51] op_sel_hi:[0,1]
	v_pk_fma_f32 v[50:51], v[34:35], v[34:35], v[50:51]
	v_mul_f32_e32 v0, v35, v35
	v_pk_add_f32 v[50:51], v[0:1], v[50:51] op_sel_hi:[0,1]
	v_pk_fma_f32 v[50:51], v[42:43], v[42:43], v[50:51]
	v_mul_f32_e32 v0, v43, v43
	v_pk_add_f32 v[50:51], v[0:1], v[50:51] op_sel_hi:[0,1]
	v_pk_fma_f32 v[50:51], v[120:121], v[120:121], v[50:51]
	v_mul_f32_e32 v0, v121, v121
	v_pk_add_f32 v[50:51], v[0:1], v[50:51] op_sel_hi:[0,1]
	v_pk_fma_f32 v[50:51], v[116:117], v[116:117], v[50:51]
	v_mul_f32_e32 v0, v117, v117
	v_pk_add_f32 v[50:51], v[0:1], v[50:51] op_sel_hi:[0,1]
	v_pk_fma_f32 v[50:51], v[106:107], v[106:107], v[50:51]
	v_mul_f32_e32 v0, v105, v105
	v_pk_add_f32 v[50:51], v[0:1], v[50:51] op_sel_hi:[0,1]
	v_pk_fma_f32 v[50:51], v[30:31], v[30:31], v[50:51]
	v_mul_f32_e32 v0, v31, v31
	v_pk_add_f32 v[50:51], v[0:1], v[50:51] op_sel_hi:[0,1]
	v_pk_fma_f32 v[50:51], v[118:119], v[118:119], v[50:51]
	v_mul_f32_e32 v0, v119, v119
	v_pk_add_f32 v[50:51], v[0:1], v[50:51] op_sel_hi:[0,1]
	v_pk_fma_f32 v[50:51], v[114:115], v[114:115], v[50:51]
	v_mul_f32_e32 v0, v115, v115
	v_pk_add_f32 v[50:51], v[0:1], v[50:51] op_sel_hi:[0,1]
	v_mul_f32_e32 v0, v135, v135
	v_pk_add_f32 v[50:51], v[0:1], v[50:51] op_sel_hi:[0,1]
	v_pk_fma_f32 v[50:51], v[134:135], v[134:135], v[50:51]
	v_permlane32_swap_b32_e32 v200, v203
	v_mov_b32_e32 v202, v50
	s_nop 1
	v_permlane32_swap_b32_e32 v50, v202
	v_mov_b32_e32 v51, v200
	v_pk_add_f32 v[50:51], v[50:51], v[202:203]
	s_mov_b32 s0, 0x3c800000
	v_pk_fma_f32 v[50:51], v[50:51], s[0:1], v[210:211] op_sel_hi:[1,0,0]
	s_mov_b32 s0, 0x800000
	v_mul_f32_e32 v0, 0x4b800000, v51
	v_cmp_gt_f32_e32 vcc, s0, v51
	v_mov_b32_e32 v133, v45
	v_mov_b32_e32 v184, v14
	v_cndmask_b32_e32 v0, v51, v0, vcc
	v_rsq_f32_e32 v0, v0
	v_mov_b32_e32 v185, v11
	v_mov_b32_e32 v152, v10
	v_mov_b32_e32 v153, v15
	v_mul_f32_e32 v51, 0x45800000, v0
	v_cndmask_b32_e32 v0, v0, v51, vcc
	v_pk_mul_f32 v[134:135], v[0:1], v[100:101] op_sel_hi:[0,1]
	v_pk_mul_f32 v[128:129], v[134:135], v[128:129]
	v_pk_mul_f32 v[134:135], v[0:1], v[12:13] op_sel_hi:[0,1]
	v_pk_mul_f32 v[130:131], v[134:135], v[130:131]
	v_pk_mul_f32 v[132:133], v[128:129], v[132:133]
	v_mov_b32_e32 v135, v129
	v_mov_b32_e32 v129, v131
	v_pk_mul_f32 v[128:129], v[128:129], v[44:45]
	v_mov_b32_e32 v134, v130
	s_waitcnt vmcnt(0)
	v_mov_b32_e32 v202, v17
	v_mov_b32_e32 v203, v18
	v_pk_fma_f32 v[122:123], v[130:131], v[122:123], v[132:133]
	v_mov_b32_e32 v132, v16
	v_mov_b32_e32 v44, v16
	v_mov_b32_e32 v45, v18
	v_mov_b32_e32 v18, v17
	v_pk_fma_f32 v[16:17], v[134:135], v[194:195], v[128:129] neg_lo:[0,0,1] neg_hi:[0,0,1]
	v_pk_mul_f32 v[134:135], v[0:1], v[184:185] op_sel_hi:[0,1]
	v_pk_mul_f32 v[152:153], v[0:1], v[152:153] op_sel_hi:[0,1]
	v_mov_b32_e32 v149, v29
	v_pk_mul_f32 v[126:127], v[134:135], v[126:127]
	v_pk_mul_f32 v[124:125], v[152:153], v[124:125]
	v_pk_mul_f32 v[148:149], v[126:127], v[148:149]
	v_mov_b32_e32 v185, v127
	v_mov_b32_e32 v127, v125
	v_pk_mul_f32 v[16:17], v[16:17], s[4:5] op_sel_hi:[1,0]
	v_mov_b32_e32 v134, v75
	v_mov_b32_e32 v135, v76
	v_pk_mul_f32 v[28:29], v[126:127], v[28:29]
	v_mov_b32_e32 v126, v74
	v_mov_b32_e32 v194, v74
	v_mov_b32_e32 v195, v76
	v_mov_b32_e32 v76, v75
	v_pk_fma_f32 v[74:75], v[124:125], v[112:113], v[148:149]
	v_cvt_pk_bf16_f32 v149, v16, v17
	v_pk_mul_f32 v[16:17], v[122:123], s[4:5] op_sel_hi:[1,0]
	v_mov_b32_e32 v184, v124
	v_cvt_pk_bf16_f32 v153, v16, v17
	v_pk_fma_f32 v[16:17], v[184:185], v[182:183], v[28:29] neg_lo:[0,0,1] neg_hi:[0,0,1]
	v_mov_b32_e32 v150, v40
	v_pk_mul_f32 v[16:17], v[16:17], s[4:5] op_sel_hi:[1,0]
	v_mov_b32_e32 v151, v49
	v_cvt_pk_bf16_f32 v148, v16, v17
	v_pk_mul_f32 v[16:17], v[74:75], s[4:5] op_sel_hi:[1,0]
	v_mov_b32_e32 v146, v48
	v_mov_b32_e32 v147, v41
	v_cvt_pk_bf16_f32 v152, v16, v17
	v_pk_mul_f32 v[16:17], v[0:1], v[150:151] op_sel_hi:[0,1]
	v_mov_b32_e32 v145, v25
	v_pk_mul_f32 v[16:17], v[16:17], v[138:139]
	v_pk_mul_f32 v[28:29], v[0:1], v[146:147] op_sel_hi:[0,1]
	v_pk_mul_f32 v[28:29], v[28:29], v[136:137]
	v_pk_mul_f32 v[74:75], v[16:17], v[144:145]
	v_mov_b32_e32 v164, v38
	v_pk_fma_f32 v[74:75], v[28:29], v[110:111], v[74:75]
	v_mov_b32_e32 v111, v17
	v_mov_b32_e32 v17, v29
	v_mov_b32_e32 v110, v28
	v_pk_mul_f32 v[16:17], v[16:17], v[24:25]
	v_mov_b32_e32 v165, v47
	v_pk_fma_f32 v[16:17], v[110:111], v[166:167], v[16:17] neg_lo:[0,0,1] neg_hi:[0,0,1]
	v_mov_b32_e32 v162, v46
	v_pk_mul_f32 v[16:17], v[16:17], s[4:5] op_sel_hi:[1,0]
	v_mov_b32_e32 v163, v39
	v_cvt_pk_bf16_f32 v147, v16, v17
	v_pk_mul_f32 v[16:17], v[74:75], s[4:5] op_sel_hi:[1,0]
	v_pk_mul_f32 v[24:25], v[0:1], v[162:163] op_sel_hi:[0,1]
	v_cvt_pk_bf16_f32 v151, v16, v17
	v_pk_mul_f32 v[16:17], v[0:1], v[164:165] op_sel_hi:[0,1]
	v_mov_b32_e32 v161, v21
	v_pk_mul_f32 v[16:17], v[16:17], v[142:143]
	v_pk_mul_f32 v[24:25], v[24:25], v[140:141]
	v_pk_mul_f32 v[28:29], v[16:17], v[160:161]
	v_mov_b32_e32 v75, v17
	v_mov_b32_e32 v17, v25
	v_mov_b32_e32 v74, v24
	v_pk_mul_f32 v[16:17], v[16:17], v[20:21]
	v_pk_fma_f32 v[28:29], v[24:25], v[108:109], v[28:29]
	v_pk_fma_f32 v[16:17], v[74:75], v[154:155], v[16:17] neg_lo:[0,0,1] neg_hi:[0,0,1]
	v_mov_b32_e32 v172, v64
	v_pk_mul_f32 v[16:17], v[16:17], s[4:5] op_sel_hi:[1,0]
	v_mov_b32_e32 v173, v69
	v_mov_b32_e32 v170, v68
	v_mov_b32_e32 v171, v65
	v_cvt_pk_bf16_f32 v146, v16, v17
	v_pk_mul_f32 v[16:17], v[28:29], s[4:5] op_sel_hi:[1,0]
	v_pk_mul_f32 v[20:21], v[170:171], v[0:1] op_sel_hi:[1,0]
	v_cvt_pk_bf16_f32 v150, v16, v17
	v_pk_mul_f32 v[16:17], v[0:1], v[172:173] op_sel_hi:[0,1]
	v_mov_b32_e32 v175, v61
	v_pk_mul_f32 v[16:17], v[16:17], v[156:157]
	v_pk_mul_f32 v[20:21], v[20:21], v[158:159]
	v_pk_mul_f32 v[24:25], v[16:17], v[174:175]
	v_mov_b32_e32 v29, v17
	v_mov_b32_e32 v17, v21
	v_mov_b32_e32 v28, v20
	v_pk_mul_f32 v[16:17], v[16:17], v[60:61]
	v_pk_fma_f32 v[24:25], v[20:21], v[168:169], v[24:25]
	v_pk_fma_f32 v[16:17], v[28:29], v[26:27], v[16:17] neg_lo:[0,0,1] neg_hi:[0,0,1]
	v_mov_b32_e32 v180, v62
	v_pk_mul_f32 v[16:17], v[16:17], s[4:5] op_sel_hi:[1,0]
	v_mov_b32_e32 v181, v67
	v_mov_b32_e32 v178, v66
	v_mov_b32_e32 v179, v63
	v_cvt_pk_bf16_f32 v157, v16, v17
	v_pk_mul_f32 v[16:17], v[24:25], s[4:5] op_sel_hi:[1,0]
	v_pk_mul_f32 v[20:21], v[178:179], v[0:1] op_sel_hi:[1,0]
	v_cvt_pk_bf16_f32 v161, v16, v17
	v_pk_mul_f32 v[16:17], v[0:1], v[180:181] op_sel_hi:[0,1]
	v_mov_b32_e32 v198, v54
	v_mov_b32_e32 v199, v57
	v_pk_mul_f32 v[16:17], v[16:17], v[176:177]
	v_pk_mul_f32 v[20:21], v[20:21], v[92:93]
	v_mov_b32_e32 v85, v56
	v_mov_b32_e32 v53, v56
	v_mov_b32_e32 v56, v55
	v_pk_mul_f32 v[24:25], v[16:17], v[198:199]
	v_mov_b32_e32 v29, v17
	v_mov_b32_e32 v17, v21
	v_mov_b32_e32 v52, v54
	v_mov_b32_e32 v28, v20
	v_pk_mul_f32 v[16:17], v[16:17], v[56:57]
	v_mov_b32_e32 v84, v55
	v_pk_fma_f32 v[16:17], v[28:29], v[52:53], v[16:17] neg_lo:[0,0,1] neg_hi:[0,0,1]
	v_pk_fma_f32 v[24:25], v[20:21], v[84:85], v[24:25]
	v_pk_mul_f32 v[16:17], v[16:17], s[4:5] op_sel_hi:[1,0]
	v_mov_b32_e32 v54, v80
	v_mov_b32_e32 v55, v89
	v_mov_b32_e32 v200, v88
	v_mov_b32_e32 v201, v81
	v_cvt_pk_bf16_f32 v156, v16, v17
	v_pk_mul_f32 v[16:17], v[24:25], s[4:5] op_sel_hi:[1,0]
	v_pk_mul_f32 v[20:21], v[200:201], v[0:1] op_sel_hi:[1,0]
	v_cvt_pk_bf16_f32 v160, v16, v17
	v_pk_mul_f32 v[16:17], v[0:1], v[54:55] op_sel_hi:[0,1]
	v_mov_b32_e32 v133, v19
	v_pk_mul_f32 v[16:17], v[16:17], v[188:189]
	v_pk_mul_f32 v[20:21], v[20:21], v[190:191]
	v_pk_mul_f32 v[24:25], v[16:17], v[132:133]
	v_mov_b32_e32 v29, v17
	v_mov_b32_e32 v17, v21
	v_mov_b32_e32 v28, v20
	v_pk_mul_f32 v[16:17], v[16:17], v[18:19]
	v_pk_fma_f32 v[24:25], v[20:21], v[202:203], v[24:25]
	v_pk_fma_f32 v[16:17], v[28:29], v[44:45], v[16:17] neg_lo:[0,0,1] neg_hi:[0,0,1]
	v_mov_b32_e32 v128, v78
	v_pk_mul_f32 v[16:17], v[16:17], s[4:5] op_sel_hi:[1,0]
	v_mov_b32_e32 v129, v87
	v_mov_b32_e32 v130, v86
	v_mov_b32_e32 v131, v79
	v_cvt_pk_bf16_f32 v155, v16, v17
	v_pk_mul_f32 v[16:17], v[24:25], s[4:5] op_sel_hi:[1,0]
	v_pk_mul_f32 v[20:21], v[130:131], v[0:1] op_sel_hi:[1,0]
	v_cvt_pk_bf16_f32 v159, v16, v17
	v_pk_mul_f32 v[16:17], v[128:129], v[0:1] op_sel_hi:[1,0]
	v_mov_b32_e32 v127, v77
	v_pk_mul_f32 v[16:17], v[16:17], v[90:91]
	v_pk_mul_f32 v[20:21], v[20:21], v[192:193]
	v_mul_f32_e32 v0, 0x4b800000, v50
	v_cmp_gt_f32_e32 vcc, s0, v50
	v_pk_mul_f32 v[24:25], v[16:17], v[126:127]
	v_mov_b32_e32 v29, v17
	v_mov_b32_e32 v17, v21
	v_cndmask_b32_e32 v0, v50, v0, vcc
	v_mov_b32_e32 v28, v20
	v_pk_mul_f32 v[16:17], v[16:17], v[76:77]
	v_rsq_f32_e32 v0, v0
	v_pk_fma_f32 v[16:17], v[28:29], v[194:195], v[16:17] neg_lo:[0,0,1] neg_hi:[0,0,1]
	v_pk_fma_f32 v[24:25], v[20:21], v[134:135], v[24:25]
	v_pk_mul_f32 v[16:17], v[16:17], s[4:5] op_sel_hi:[1,0]
	v_mov_b32_e32 v102, v2
	v_cvt_pk_bf16_f32 v154, v16, v17
	v_pk_mul_f32 v[16:17], v[24:25], s[4:5] op_sel_hi:[1,0]
	v_mov_b32_e32 v103, v5
	v_cvt_pk_bf16_f32 v158, v16, v17
	v_mul_f32_e32 v16, 0x45800000, v0
	v_cndmask_b32_e32 v0, v0, v16, vcc
	v_pk_mul_f32 v[54:55], v[80:81], v[0:1] op_sel_hi:[1,0]
	v_pk_mul_f32 v[20:21], v[88:89], v[0:1] op_sel_hi:[1,0]
	v_pk_mul_f32 v[24:25], v[66:67], v[0:1] op_sel_hi:[1,0]
	v_pk_mul_f32 v[54:55], v[54:55], v[196:197]
	v_pk_mul_f32 v[20:21], v[20:21], v[72:73]
	v_pk_mul_f32 v[24:25], v[24:25], v[58:59]
	v_pk_mul_f32 v[58:59], v[62:63], v[0:1] op_sel_hi:[1,0]
	v_pk_mul_f32 v[62:63], v[64:65], v[0:1] op_sel_hi:[1,0]
	v_pk_mul_f32 v[64:65], v[44:45], v[54:55]
	v_pk_mul_f32 v[14:15], v[14:15], v[0:1] op_sel_hi:[1,0]
	v_pk_fma_f32 v[64:65], v[18:19], v[20:21], v[64:65]
	v_pk_mul_f32 v[18:19], v[18:19], v[54:55]
	v_pk_mul_f32 v[10:11], v[10:11], v[0:1] op_sel_hi:[1,0]
	v_pk_mul_f32 v[38:39], v[38:39], v[0:1] op_sel_hi:[1,0]
	v_pk_mul_f32 v[14:15], v[14:15], v[114:115]
	v_pk_fma_f32 v[18:19], v[44:45], v[20:21], v[18:19] neg_lo:[0,0,1] neg_hi:[0,0,1]
	v_pk_mul_f32 v[58:59], v[58:59], v[70:71]
	v_pk_mul_f32 v[46:47], v[46:47], v[0:1] op_sel_hi:[1,0]
	v_pk_mul_f32 v[10:11], v[10:11], v[116:117]
	v_pk_mul_f32 v[30:31], v[38:39], v[30:31]
	v_pk_mul_f32 v[38:39], v[40:41], v[0:1] op_sel_hi:[1,0]
	v_pk_mul_f32 v[40:41], v[100:101], v[0:1] op_sel_hi:[1,0]
	v_pk_mul_f32 v[12:13], v[12:13], v[0:1] op_sel_hi:[1,0]
	v_pk_mul_f32 v[70:71], v[96:97], v[14:15]
	v_pk_mul_f32 v[18:19], v[18:19], s[4:5] op_sel_hi:[1,0]
	v_pk_mul_f32 v[42:43], v[46:47], v[42:43]
	v_pk_mul_f32 v[46:47], v[48:49], v[0:1] op_sel_hi:[1,0]
	v_pk_mul_f32 v[38:39], v[38:39], v[118:119]
	v_pk_mul_f32 v[40:41], v[40:41], v[104:105]
	v_pk_mul_f32 v[12:13], v[12:13], v[106:107]
	v_pk_fma_f32 v[70:71], v[8:9], v[10:11], v[70:71]
	v_cvt_pk_bf16_f32 v163, v18, v19
	v_pk_mul_f32 v[18:19], v[64:65], s[4:5] op_sel_hi:[1,0]
	v_pk_mul_f32 v[8:9], v[8:9], v[14:15]
	v_mov_b32_e32 v99, v4
	v_pk_mul_f32 v[46:47], v[46:47], v[120:121]
	v_pk_mul_f32 v[74:75], v[40:41], v[102:103]
	v_cvt_pk_bf16_f32 v167, v18, v19
	v_pk_mul_f32 v[18:19], v[32:33], v[38:39]
	v_pk_fma_f32 v[8:9], v[96:97], v[10:11], v[8:9] neg_lo:[0,0,1] neg_hi:[0,0,1]
	v_mov_b32_e32 v11, v41
	v_mov_b32_e32 v15, v4
	v_mov_b32_e32 v41, v13
	v_mov_b32_e32 v4, v3
	v_mov_b32_e32 v98, v3
	v_pk_mul_f32 v[66:67], v[6:7], v[38:39]
	v_pk_fma_f32 v[6:7], v[6:7], v[46:47], v[18:19] neg_lo:[0,0,1] neg_hi:[0,0,1]
	v_mov_b32_e32 v10, v12
	v_mov_b32_e32 v14, v2
	v_pk_mul_f32 v[2:3], v[40:41], v[4:5]
	v_pk_mul_f32 v[34:35], v[62:63], v[34:35]
	v_pk_mul_f32 v[62:63], v[22:23], v[30:31]
	v_pk_mul_f32 v[6:7], v[6:7], s[4:5] op_sel_hi:[1,0]
	v_pk_fma_f32 v[2:3], v[10:11], v[14:15], v[2:3] neg_lo:[0,0,1] neg_hi:[0,0,1]
	v_pk_fma_f32 v[62:63], v[36:37], v[42:43], v[62:63]
	v_pk_mul_f32 v[2:3], v[2:3], s[4:5] op_sel_hi:[1,0]
	v_cvt_pk_bf16_f32 v171, v6, v7
	v_pk_mul_f32 v[6:7], v[70:71], s[4:5] op_sel_hi:[1,0]
	v_cvt_pk_bf16_f32 v173, v2, v3
	v_pk_mul_f32 v[2:3], v[62:63], s[4:5] op_sel_hi:[1,0]
	v_cvt_pk_bf16_f32 v176, v6, v7
	v_add_u32_e32 v6, s77, v204
	v_cvt_pk_bf16_f32 v174, v2, v3
	v_lshlrev_b32_e32 v2, 1, v204
	v_lshrrev_b32_e32 v7, 1, v6
	v_pk_mul_f32 v[16:17], v[86:87], v[0:1] op_sel_hi:[1,0]
	v_pk_mul_f32 v[28:29], v[68:69], v[0:1] op_sel_hi:[1,0]
	v_pk_mul_f32 v[50:51], v[78:79], v[0:1] op_sel_hi:[1,0]
	s_and_b64 s[0:1], s[40:41], exec
	v_and_b32_e32 v0, 19, v204
	v_and_b32_e32 v2, 8, v2
	v_and_b32_e32 v3, 4, v7
	s_cselect_b32 s24, 64, 0
	v_or3_b32 v0, v2, v0, v3
	s_lshl_b32 s0, s24, 1
	v_lshlrev_b32_e32 v2, 7, v0
	v_lshrrev_b32_e32 v0, 1, v0
	s_add_u32 s0, s18, s0
	v_bitop3_b32 v3, v0, v206, 7 bitop3:0x6c
	s_addc_u32 s1, s19, 0
	v_lshl_or_b32 v213, v3, 4, v2
	v_or_b32_e32 v3, 2, v206
	s_add_u32 s18, s0, 0x4400500
	v_bitop3_b32 v3, v0, v3, 7 bitop3:0x6c
	s_addc_u32 s19, s1, 0
	s_lshl_b32 s22, s30, 7
	v_lshl_or_b32 v240, v3, 4, v2
	v_or_b32_e32 v3, 4, v206
	s_or_b32 s22, s24, s22
	v_bitop3_b32 v3, v0, v3, 7 bitop3:0x6c
	s_mul_i32 s25, s22, 0x1080
	v_lshl_or_b32 v241, v3, 4, v2
	v_or_b32_e32 v3, 6, v206
	s_mov_b32 s22, 0x41f00000
	v_bitop3_b32 v0, v0, v3, 7 bitop3:0x6c
	v_cmp_gt_f32_e32 vcc, s22, v207
	v_pk_mul_f32 v[50:51], v[50:51], v[186:187]
	v_lshl_or_b32 v242, v0, 4, v2
	v_cndmask_b32_e64 v0, 0, 1, vcc
	v_pk_mul_f32 v[16:17], v[16:17], v[82:83]
	v_pk_mul_f32 v[48:49], v[194:195], v[50:51]
	v_pk_fma_f32 v[66:67], v[32:33], v[46:47], v[66:67]
	v_pk_mul_f32 v[50:51], v[76:77], v[50:51]
	v_readfirstlane_b32 s22, v0
	v_pk_fma_f32 v[48:49], v[76:77], v[16:17], v[48:49]
	v_pk_fma_f32 v[74:75], v[12:13], v[98:99], v[74:75]
	v_pk_fma_f32 v[16:17], v[194:195], v[16:17], v[50:51] neg_lo:[0,0,1] neg_hi:[0,0,1]
	v_pk_mul_f32 v[8:9], v[8:9], s[4:5] op_sel_hi:[1,0]
	v_pk_mul_f32 v[4:5], v[66:67], s[4:5] op_sel_hi:[1,0]
	s_bitcmp1_b32 s22, 0
	v_pk_mul_f32 v[68:69], v[52:53], v[58:59]
	v_pk_mul_f32 v[16:17], v[16:17], s[4:5] op_sel_hi:[1,0]
	v_pk_mul_f32 v[20:21], v[56:57], v[58:59]
	v_cvt_pk_bf16_f32 v172, v8, v9
	v_pk_mul_f32 v[8:9], v[74:75], s[4:5] op_sel_hi:[1,0]
	v_cvt_pk_bf16_f32 v175, v4, v5
	s_cselect_b64 s[22:23], -1, 0
	v_ashrrev_i32_e32 v4, 6, v6
	v_bfe_u32 v0, v204, 3, 3
	v_pk_mul_f32 v[28:29], v[28:29], v[94:95]
	v_pk_fma_f32 v[68:69], v[56:57], v[24:25], v[68:69]
	v_pk_fma_f32 v[20:21], v[52:53], v[24:25], v[20:21] neg_lo:[0,0,1] neg_hi:[0,0,1]
	v_pk_mul_f32 v[24:25], v[60:61], v[34:35]
	v_cvt_pk_bf16_f32 v162, v16, v17
	v_pk_mul_f32 v[16:17], v[48:49], s[4:5] op_sel_hi:[1,0]
	v_cvt_pk_bf16_f32 v177, v8, v9
	s_xor_b64 s[30:31], s[22:23], -1
	v_readlane_b32 s22, v253, 47
	v_lshl_or_b32 v8, v4, 3, v0
	v_pk_mul_f32 v[72:73], v[26:27], v[34:35]
	v_pk_fma_f32 v[24:25], v[26:27], v[28:29], v[24:25] neg_lo:[0,0,1] neg_hi:[0,0,1]
	v_cvt_pk_bf16_f32 v166, v16, v17
	v_pk_mul_f32 v[16:17], v[36:37], v[30:31]
	s_add_u32 s22, s22, s25
	v_readlane_b32 s23, v253, 48
	v_lshrrev_b32_e32 v9, 1, v8
	v_mov_b64_e32 v[2:3], s[18:19]
	v_lshlrev_b32_e32 v4, 10, v4
	v_lshlrev_b32_e32 v5, 4, v205
	v_pk_fma_f32 v[72:73], v[60:61], v[28:29], v[72:73]
	v_pk_mul_f32 v[20:21], v[20:21], s[4:5] op_sel_hi:[1,0]
	v_pk_mul_f32 v[24:25], v[24:25], s[4:5] op_sel_hi:[1,0]
	v_pk_fma_f32 v[16:17], v[22:23], v[42:43], v[16:17] neg_lo:[0,0,1] neg_hi:[0,0,1]
	s_addc_u32 s23, s23, 0
	v_xor_b32_e32 v0, v9, v204
	v_mad_i64_i32 v[2:3], s[18:19], v8, s5, v[2:3]
	v_add3_u32 v243, 0, v4, v5
	v_cvt_pk_bf16_f32 v164, v20, v21
	v_cvt_pk_bf16_f32 v165, v24, v25
	v_pk_mul_f32 v[20:21], v[68:69], s[4:5] op_sel_hi:[1,0]
	v_pk_mul_f32 v[24:25], v[72:73], s[4:5] op_sel_hi:[1,0]
	v_pk_mul_f32 v[16:17], v[16:17], s[4:5] op_sel_hi:[1,0]
	v_lshlrev_b32_e32 v0, 4, v0
	v_readfirstlane_b32 s18, v243
	v_mov_b64_e32 v[4:5], s[22:23]
	s_movk_i32 s4, 0x1080
	v_and_b32_e32 v0, 0x70, v0
	s_mov_b32 m0, s18
	v_mad_i64_i32 v[4:5], s[18:19], v8, s4, v[4:5]
	v_lshl_add_u64 v[2:3], v[2:3], 0, v[0:1]
	v_lshl_add_u64 v[4:5], v[4:5], 0, v[0:1]
	v_add_u32_e32 v0, 0x2000, v243
	global_load_lds_dwordx4 v[2:3], off
	v_readfirstlane_b32 s18, v0
	s_mov_b32 m0, s18
	s_mov_b64 s[18:19], 0x53000
	v_add_u32_e32 v0, 0x4000, v243
	v_lshl_add_u64 v[2:3], v[2:3], 0, s[18:19]
	v_readfirstlane_b32 s18, v0
	v_add_u32_e32 v0, 0x6000, v243
	global_load_lds_dwordx4 v[4:5], off
	s_mov_b32 m0, s18
	v_readfirstlane_b32 s18, v0
	global_load_lds_dwordx4 v[2:3], off
	v_lshl_add_u64 v[2:3], v[4:5], 0, s[26:27]
	s_mov_b32 m0, s18
	v_readlane_b32 s18, v254, 35
	global_load_lds_dwordx4 v[2:3], off
	s_add_i32 s18, s18, s24
	s_lshl_b32 s19, s44, 7
	s_add_i32 s18, s18, s19
	v_bfe_u32 v0, v6, 1, 3
	v_bitop3_b32 v2, v7, v206, 7 bitop3:0x6c
	s_mulk_i32 s18, 0x1080
	v_lshlrev_b32_e32 v244, 4, v2
	v_bitop3_b32 v2, v206, v0, 2 bitop3:0x36
	s_add_u32 s18, s74, s18
	v_lshlrev_b32_e32 v245, 4, v2
	v_bitop3_b32 v2, v206, v0, 4 bitop3:0x36
	s_addc_u32 s19, s75, 0
	v_lshlrev_b32_e32 v246, 4, v2
	v_mov_b64_e32 v[2:3], s[18:19]
	v_cvt_pk_bf16_f32 v170, v16, v17
	v_bitop3_b32 v0, v206, v0, 6 bitop3:0x36
	v_mad_i64_i32 v[214:215], s[18:19], v8, s4, v[2:3]
	v_mov_b64_e32 v[2:3], s[0:1]
	v_mov_b32_e32 v16, v1
	v_mov_b32_e32 v17, v1
	v_cvt_pk_bf16_f32 v168, v20, v21
	v_cvt_pk_bf16_f32 v169, v24, v25
	v_lshlrev_b32_e32 v247, 4, v0
	v_bitop3_b32 v0, v9, 7, v204 bitop3:0x48
	v_mad_i64_i32 v[216:217], s[0:1], v8, s5, v[2:3]
	v_mov_b32_e32 v2, v1
	v_mov_b32_e32 v3, v1
	v_mov_b32_e32 v4, v1
	v_mov_b32_e32 v5, v1
	v_mov_b32_e32 v6, v1
	v_mov_b32_e32 v7, v1
	v_mov_b32_e32 v8, v1
	v_mov_b32_e32 v9, v1
	v_mov_b32_e32 v10, v1
	v_mov_b32_e32 v11, v1
	v_mov_b32_e32 v12, v1
	v_mov_b32_e32 v13, v1
	v_mov_b32_e32 v14, v1
	v_mov_b32_e32 v15, v1
	v_bfrev_b32_e32 v66, 1
	v_mov_b64_e32 v[32:33], v[16:17]
	v_mov_b64_e32 v[48:49], v[16:17]
	v_mov_b64_e32 v[64:65], v[16:17]
	s_mov_b32 s42, 0x4400000
	s_mov_b32 s28, 0
	v_lshlrev_b32_e32 v0, 4, v0
	s_movk_i32 s4, 0x14c0
	v_mov_b32_e32 v248, 0
	s_mov_b32 s0, 0xc000
	v_mov_b64_e32 v[30:31], v[14:15]
	v_mov_b64_e32 v[28:29], v[12:13]
	v_mov_b64_e32 v[26:27], v[10:11]
	v_mov_b64_e32 v[24:25], v[8:9]
	v_mov_b64_e32 v[22:23], v[6:7]
	v_mov_b64_e32 v[20:21], v[4:5]
	v_mov_b64_e32 v[18:19], v[2:3]
	v_mov_b64_e32 v[46:47], v[14:15]
	v_mov_b64_e32 v[44:45], v[12:13]
	v_mov_b64_e32 v[42:43], v[10:11]
	v_mov_b64_e32 v[40:41], v[8:9]
	v_mov_b64_e32 v[38:39], v[6:7]
	v_mov_b64_e32 v[36:37], v[4:5]
	v_mov_b64_e32 v[34:35], v[2:3]
	v_mov_b64_e32 v[62:63], v[14:15]
	v_mov_b64_e32 v[60:61], v[12:13]
	v_mov_b64_e32 v[58:59], v[10:11]
	v_mov_b64_e32 v[56:57], v[8:9]
	v_mov_b64_e32 v[54:55], v[6:7]
	v_mov_b64_e32 v[52:53], v[4:5]
	v_mov_b64_e32 v[50:51], v[2:3]
	v_mov_b32_e32 v249, 0
	v_mov_b32_e32 v250, 0
	v_mov_b32_e32 v251, 0
	v_mov_b32_e32 v67, v66
	v_mov_b32_e32 v68, v66
	v_mov_b32_e32 v69, v66
	v_mov_b32_e32 v70, v66
	v_mov_b32_e32 v71, v66
	v_mov_b32_e32 v72, v66
	v_mov_b32_e32 v73, v66
	v_mov_b32_e32 v74, v66
	v_mov_b32_e32 v75, v66
	v_mov_b32_e32 v76, v66
	v_mov_b32_e32 v77, v66
	v_mov_b32_e32 v78, v66
	v_mov_b32_e32 v79, v66
	v_mov_b32_e32 v80, v66
	v_mov_b32_e32 v81, v66
	v_mov_b32_e32 v82, v66
	v_mov_b32_e32 v83, v66
	v_mov_b32_e32 v84, v66
	v_mov_b32_e32 v85, v66
	v_mov_b32_e32 v86, v66
	v_mov_b32_e32 v87, v66
	v_mov_b32_e32 v88, v66
	v_mov_b32_e32 v89, v66
	v_mov_b32_e32 v90, v66
	v_mov_b32_e32 v91, v66
	v_mov_b32_e32 v92, v66
	v_mov_b32_e32 v93, v66
	v_mov_b32_e32 v94, v66
	v_mov_b32_e32 v95, v66
	v_mov_b32_e32 v96, v66
	v_mov_b32_e32 v97, v66
	s_and_b64 vcc, exec, s[30:31]
	s_cbranch_vccz .La_fast
	s_branch .LBB0_179

.La_fast:
	v_add_u32_e32 v130, v212, v244
	v_add_u32_e32 v131, v212, v245
	v_add_u32_e32 v132, v212, v246
	v_add_u32_e32 v133, v212, v247
	s_mov_b32 s28, 0
	s_waitcnt vmcnt(0)
	s_barrier
	v_add_u32_e32 v142, 0x8000, v243
	v_lshl_add_u64 v[136:137], v[216:217], 0, v[0:1]
	s_mov_b64 s[18:19], 0x44a6500
	v_readfirstlane_b32 s1, v142
	v_lshl_add_u64 v[138:139], v[136:137], 0, s[18:19]
	s_mov_b32 m0, s1
	v_add_u32_e32 v142, 0x2000, v142
	global_load_lds_dwordx4 v[138:139], off
	v_lshl_add_u64 v[138:139], v[214:215], 0, v[0:1]
	s_mov_b64 s[18:19], 0x11600100
	v_readfirstlane_b32 s1, v142
	v_lshl_add_u64 v[140:141], v[138:139], 0, s[18:19]
	s_mov_b32 m0, s1
	v_add_u32_e32 v142, 0xc000, v243
	global_load_lds_dwordx4 v[140:141], off
	s_mov_b64 s[18:19], 0x44f9500
	v_readfirstlane_b32 s1, v142
	v_lshl_add_u64 v[136:137], v[136:137], 0, s[18:19]
	s_mov_b32 m0, s1
	s_mov_b64 s[18:19], 0x11600180
	global_load_lds_dwordx4 v[136:137], off
	v_lshl_add_u64 v[136:137], v[138:139], 0, s[18:19]
	v_add_u32_e32 v142, 0x2000, v142
	s_nop 0
	v_readfirstlane_b32 s1, v142
	s_mov_b32 m0, s1
	s_nop 0
	global_load_lds_dwordx4 v[136:137], off
	ds_read_b128 v[194:197], v213
	ds_read_b128 v[198:201], v240
	ds_read_b128 v[202:205], v241
	ds_read_b128 v[206:209], v242
	ds_read_b128 v[178:181], v130 offset:8192
	ds_read_b128 v[182:185], v130 offset:12288
	ds_read_b128 v[186:189], v131 offset:8192
	ds_read_b128 v[190:193], v131 offset:12288
	v_mov_b32_e32 v114, 0
	v_mov_b32_e32 v115, 0
	v_mov_b32_e32 v116, 0
	v_mov_b32_e32 v117, 0
	v_mov_b32_e32 v118, 0
	v_mov_b32_e32 v119, 0
	v_mov_b32_e32 v120, 0
	v_mov_b32_e32 v121, 0
	s_waitcnt lgkmcnt(0)
	v_mfma_f32_32x32x16_bf16 v[98:113], v[194:197], v[154:157], 0
	v_mfma_f32_32x32x16_bf16 v[98:113], v[198:201], v[158:161], v[98:113]
	v_mfma_f32_32x32x16_bf16 v[98:113], v[202:205], v[146:149], v[98:113]
	v_mfma_f32_32x32x16_bf16 v[98:113], v[206:209], v[150:153], v[98:113]
	s_nop 10
.La_loop:
	v_mfma_f32_32x32x16_bf16 v[18:33], v[178:181], v[114:117], v[18:33]
	v_exp_f32_e32 v98, v98
	v_exp_f32_e32 v99, v99
	v_exp_f32_e32 v100, v100
	v_exp_f32_e32 v101, v101
	v_mfma_f32_32x32x16_bf16 v[2:17], v[182:185], v[114:117], v[2:17]
	v_add_f32_e32 v134, v99, v98
	v_exp_f32_e32 v102, v102
	v_add_f32_e32 v134, v100, v134
	v_exp_f32_e32 v103, v103
	v_mfma_f32_32x32x16_bf16 v[18:33], v[186:189], v[118:121], v[18:33]
	v_add_f32_e32 v134, v101, v134
	v_exp_f32_e32 v104, v104
	v_add_f32_e32 v134, v102, v134
	v_exp_f32_e32 v105, v105
	v_mfma_f32_32x32x16_bf16 v[2:17], v[190:193], v[118:121], v[2:17]
	ds_read_b128 v[178:181], v130 offset:8192
	ds_read_b128 v[182:185], v130 offset:12288
	ds_read_b128 v[186:189], v131 offset:8192
	ds_read_b128 v[190:193], v131 offset:12288
	v_add_f32_e32 v134, v103, v134
	v_cvt_pk_bf16_f32 v98, v98, v99
	v_exp_f32_e32 v106, v106
	v_add_f32_e32 v134, v104, v134
	v_mfma_f32_32x32x16_bf16 v[114:129], v[194:197], v[162:165], 0
	v_cvt_pk_bf16_f32 v99, v100, v101
	v_exp_f32_e32 v107, v107
	v_add_f32_e32 v134, v105, v134
	v_cvt_pk_bf16_f32 v100, v102, v103
	v_mfma_f32_32x32x16_bf16 v[114:129], v[198:201], v[166:169], v[114:129]
	v_exp_f32_e32 v108, v108
	v_add_f32_e32 v134, v106, v134
	v_cvt_pk_bf16_f32 v101, v104, v105
	v_exp_f32_e32 v109, v109
	v_mfma_f32_32x32x16_bf16 v[114:129], v[202:205], v[170:173], v[114:129]
	v_add_f32_e32 v134, v107, v134
	v_exp_f32_e32 v110, v110
	v_add_f32_e32 v134, v108, v134
	v_exp_f32_e32 v111, v111
	v_mfma_f32_32x32x16_bf16 v[114:129], v[206:209], v[174:177], v[114:129]
	ds_read_b128 v[194:197], v213 offset:4096
	ds_read_b128 v[198:201], v240 offset:4096
	ds_read_b128 v[202:205], v241 offset:4096
	ds_read_b128 v[206:209], v242 offset:4096
	v_add_f32_e32 v134, v109, v134
	v_exp_f32_e32 v112, v112
	v_add_f32_e32 v134, v110, v134
	v_exp_f32_e32 v113, v113
	v_add_f32_e32 v134, v111, v134
	v_cvt_pk_bf16_f32 v102, v106, v107
	v_add_f32_e32 v134, v112, v134
	v_cvt_pk_bf16_f32 v103, v108, v109
	v_add_f32_e32 v134, v113, v134
	v_cvt_pk_bf16_f32 v104, v110, v111
	v_add_f32_e32 v251, v251, v134
	v_cvt_pk_bf16_f32 v105, v112, v113
	s_waitcnt lgkmcnt(4)
	v_mfma_f32_32x32x16_bf16 v[50:65], v[178:181], v[98:101], v[50:65]
	v_exp_f32_e32 v114, v114
	v_exp_f32_e32 v115, v115
	v_exp_f32_e32 v116, v116
	v_exp_f32_e32 v117, v117
	v_mfma_f32_32x32x16_bf16 v[34:49], v[182:185], v[98:101], v[34:49]
	v_add_f32_e32 v134, v115, v114
	v_exp_f32_e32 v118, v118
	v_add_f32_e32 v134, v116, v134
	v_exp_f32_e32 v119, v119
	v_mfma_f32_32x32x16_bf16 v[50:65], v[186:189], v[102:105], v[50:65]
	v_add_f32_e32 v134, v117, v134
	v_exp_f32_e32 v120, v120
	v_add_f32_e32 v134, v118, v134
	v_exp_f32_e32 v121, v121
	v_mfma_f32_32x32x16_bf16 v[34:49], v[190:193], v[102:105], v[34:49]
	v_add_f32_e32 v134, v119, v134
	v_cvt_pk_bf16_f32 v114, v114, v115
	v_exp_f32_e32 v122, v122
	v_add_f32_e32 v134, v120, v134
	s_waitcnt lgkmcnt(0)
	v_mfma_f32_32x32x16_bf16 v[98:113], v[194:197], v[154:157], 0
	v_cvt_pk_bf16_f32 v115, v116, v117
	v_exp_f32_e32 v123, v123
	v_add_f32_e32 v134, v121, v134
	v_cvt_pk_bf16_f32 v116, v118, v119
	v_mfma_f32_32x32x16_bf16 v[98:113], v[198:201], v[158:161], v[98:113]
	v_exp_f32_e32 v124, v124
	v_add_f32_e32 v134, v122, v134
	v_cvt_pk_bf16_f32 v117, v120, v121
	v_exp_f32_e32 v125, v125
	v_mfma_f32_32x32x16_bf16 v[98:113], v[202:205], v[146:149], v[98:113]
	v_add_f32_e32 v134, v123, v134
	v_exp_f32_e32 v126, v126
	v_add_f32_e32 v134, v124, v134
	v_exp_f32_e32 v127, v127
	v_mfma_f32_32x32x16_bf16 v[98:113], v[206:209], v[150:153], v[98:113]
	v_add_f32_e32 v134, v125, v134
	v_exp_f32_e32 v128, v128
	v_add_f32_e32 v134, v126, v134
	v_exp_f32_e32 v129, v129
	v_add_f32_e32 v134, v127, v134
	v_cvt_pk_bf16_f32 v118, v122, v123
	v_add_f32_e32 v134, v128, v134
	v_cvt_pk_bf16_f32 v119, v124, v125
	v_add_f32_e32 v134, v129, v134
	v_cvt_pk_bf16_f32 v120, v126, v127
	v_add_f32_e32 v250, v250, v134
	v_cvt_pk_bf16_f32 v121, v128, v129
	v_mfma_f32_32x32x16_bf16 v[18:33], v[178:181], v[114:117], v[18:33]
	v_exp_f32_e32 v98, v98
	v_exp_f32_e32 v99, v99
	v_exp_f32_e32 v100, v100
	v_exp_f32_e32 v101, v101
	v_mfma_f32_32x32x16_bf16 v[2:17], v[182:185], v[114:117], v[2:17]
	v_add_f32_e32 v134, v99, v98
	v_exp_f32_e32 v102, v102
	v_add_f32_e32 v134, v100, v134
	v_exp_f32_e32 v103, v103
	v_mfma_f32_32x32x16_bf16 v[18:33], v[186:189], v[118:121], v[18:33]
	v_add_f32_e32 v134, v101, v134
	v_exp_f32_e32 v104, v104
	v_add_f32_e32 v134, v102, v134
	v_exp_f32_e32 v105, v105
	v_mfma_f32_32x32x16_bf16 v[2:17], v[190:193], v[118:121], v[2:17]
	ds_read_b128 v[178:181], v132 offset:8192
	ds_read_b128 v[182:185], v132 offset:12288
	ds_read_b128 v[186:189], v133 offset:8192
	ds_read_b128 v[190:193], v133 offset:12288
	v_add_f32_e32 v134, v103, v134
	v_cvt_pk_bf16_f32 v98, v98, v99
	v_exp_f32_e32 v106, v106
	v_add_f32_e32 v134, v104, v134
	v_mfma_f32_32x32x16_bf16 v[114:129], v[194:197], v[162:165], 0
	v_cvt_pk_bf16_f32 v99, v100, v101
	v_exp_f32_e32 v107, v107
	v_add_f32_e32 v134, v105, v134
	v_cvt_pk_bf16_f32 v100, v102, v103
	v_mfma_f32_32x32x16_bf16 v[114:129], v[198:201], v[166:169], v[114:129]
	v_exp_f32_e32 v108, v108
	v_add_f32_e32 v134, v106, v134
	v_cvt_pk_bf16_f32 v101, v104, v105
	v_exp_f32_e32 v109, v109
	v_mfma_f32_32x32x16_bf16 v[114:129], v[202:205], v[170:173], v[114:129]
	v_add_f32_e32 v134, v107, v134
	v_exp_f32_e32 v110, v110
	v_add_f32_e32 v134, v108, v134
	v_exp_f32_e32 v111, v111
	v_mfma_f32_32x32x16_bf16 v[114:129], v[206:209], v[174:177], v[114:129]
	ds_read_b128 v[194:197], v213 offset:16384
	ds_read_b128 v[198:201], v240 offset:16384
	ds_read_b128 v[202:205], v241 offset:16384
	ds_read_b128 v[206:209], v242 offset:16384
	v_add_f32_e32 v134, v109, v134
	v_exp_f32_e32 v112, v112
	v_add_f32_e32 v134, v110, v134
	v_exp_f32_e32 v113, v113
	v_add_f32_e32 v134, v111, v134
	v_cvt_pk_bf16_f32 v102, v106, v107
	v_add_f32_e32 v134, v112, v134
	v_cvt_pk_bf16_f32 v103, v108, v109
	v_add_f32_e32 v134, v113, v134
	v_cvt_pk_bf16_f32 v104, v110, v111
	v_add_f32_e32 v251, v251, v134
	v_cvt_pk_bf16_f32 v105, v112, v113
	s_waitcnt lgkmcnt(4)
	v_mfma_f32_32x32x16_bf16 v[50:65], v[178:181], v[98:101], v[50:65]
	v_exp_f32_e32 v114, v114
	v_exp_f32_e32 v115, v115
	v_exp_f32_e32 v116, v116
	v_exp_f32_e32 v117, v117
	v_mfma_f32_32x32x16_bf16 v[34:49], v[182:185], v[98:101], v[34:49]
	v_add_f32_e32 v134, v115, v114
	v_exp_f32_e32 v118, v118
	v_add_f32_e32 v134, v116, v134
	v_exp_f32_e32 v119, v119
	v_mfma_f32_32x32x16_bf16 v[50:65], v[186:189], v[102:105], v[50:65]
	v_add_f32_e32 v134, v117, v134
	v_exp_f32_e32 v120, v120
	v_add_f32_e32 v134, v118, v134
	v_exp_f32_e32 v121, v121
	v_mfma_f32_32x32x16_bf16 v[34:49], v[190:193], v[102:105], v[34:49]
	v_add_f32_e32 v134, v119, v134
	v_cvt_pk_bf16_f32 v114, v114, v115
	v_exp_f32_e32 v122, v122
	v_add_f32_e32 v134, v120, v134
	s_waitcnt lgkmcnt(0)
	v_mfma_f32_32x32x16_bf16 v[98:113], v[194:197], v[154:157], 0
	v_cvt_pk_bf16_f32 v115, v116, v117
	v_exp_f32_e32 v123, v123
	v_add_f32_e32 v134, v121, v134
	v_cvt_pk_bf16_f32 v116, v118, v119
	v_mfma_f32_32x32x16_bf16 v[98:113], v[198:201], v[158:161], v[98:113]
	v_exp_f32_e32 v124, v124
	v_add_f32_e32 v134, v122, v134
	v_cvt_pk_bf16_f32 v117, v120, v121
	v_exp_f32_e32 v125, v125
	v_mfma_f32_32x32x16_bf16 v[98:113], v[202:205], v[146:149], v[98:113]
	v_add_f32_e32 v134, v123, v134
	v_exp_f32_e32 v126, v126
	v_add_f32_e32 v134, v124, v134
	v_exp_f32_e32 v127, v127
	v_mfma_f32_32x32x16_bf16 v[98:113], v[206:209], v[150:153], v[98:113]
	v_add_f32_e32 v134, v125, v134
	v_exp_f32_e32 v128, v128
	v_add_f32_e32 v134, v126, v134
	v_exp_f32_e32 v129, v129
	v_add_f32_e32 v134, v127, v134
	v_cvt_pk_bf16_f32 v118, v122, v123
	v_add_f32_e32 v134, v128, v134
	v_cvt_pk_bf16_f32 v119, v124, v125
	v_add_f32_e32 v134, v129, v134
	v_cvt_pk_bf16_f32 v120, v126, v127
	v_add_f32_e32 v250, v250, v134
	v_cvt_pk_bf16_f32 v121, v128, v129
	v_mfma_f32_32x32x16_bf16 v[18:33], v[178:181], v[114:117], v[18:33]
	v_exp_f32_e32 v98, v98
	v_exp_f32_e32 v99, v99
	v_exp_f32_e32 v100, v100
	v_exp_f32_e32 v101, v101
	v_mfma_f32_32x32x16_bf16 v[2:17], v[182:185], v[114:117], v[2:17]
	v_add_f32_e32 v134, v99, v98
	v_exp_f32_e32 v102, v102
	v_add_f32_e32 v134, v100, v134
	v_exp_f32_e32 v103, v103
	v_mfma_f32_32x32x16_bf16 v[18:33], v[186:189], v[118:121], v[18:33]
	v_add_f32_e32 v134, v101, v134
	v_exp_f32_e32 v104, v104
	v_add_f32_e32 v134, v102, v134
	v_exp_f32_e32 v105, v105
	v_mfma_f32_32x32x16_bf16 v[2:17], v[190:193], v[118:121], v[2:17]
	ds_read_b128 v[178:181], v130 offset:24576
	ds_read_b128 v[182:185], v130 offset:28672
	ds_read_b128 v[186:189], v131 offset:24576
	ds_read_b128 v[190:193], v131 offset:28672
	v_add_f32_e32 v134, v103, v134
	v_cvt_pk_bf16_f32 v98, v98, v99
	v_exp_f32_e32 v106, v106
	v_add_f32_e32 v134, v104, v134
	v_mfma_f32_32x32x16_bf16 v[114:129], v[194:197], v[162:165], 0
	v_cvt_pk_bf16_f32 v99, v100, v101
	v_exp_f32_e32 v107, v107
	v_add_f32_e32 v134, v105, v134
	v_cvt_pk_bf16_f32 v100, v102, v103
	v_mfma_f32_32x32x16_bf16 v[114:129], v[198:201], v[166:169], v[114:129]
	v_exp_f32_e32 v108, v108
	v_add_f32_e32 v134, v106, v134
	v_cvt_pk_bf16_f32 v101, v104, v105
	v_exp_f32_e32 v109, v109
	v_mfma_f32_32x32x16_bf16 v[114:129], v[202:205], v[170:173], v[114:129]
	v_add_f32_e32 v134, v107, v134
	v_exp_f32_e32 v110, v110
	v_add_f32_e32 v134, v108, v134
	v_exp_f32_e32 v111, v111
	v_mfma_f32_32x32x16_bf16 v[114:129], v[206:209], v[174:177], v[114:129]
	ds_read_b128 v[194:197], v213 offset:20480
	ds_read_b128 v[198:201], v240 offset:20480
	ds_read_b128 v[202:205], v241 offset:20480
	ds_read_b128 v[206:209], v242 offset:20480
	v_add_f32_e32 v134, v109, v134
	v_exp_f32_e32 v112, v112
	v_add_f32_e32 v134, v110, v134
	v_exp_f32_e32 v113, v113
	v_add_f32_e32 v134, v111, v134
	v_cvt_pk_bf16_f32 v102, v106, v107
	v_add_f32_e32 v134, v112, v134
	v_cvt_pk_bf16_f32 v103, v108, v109
	v_add_f32_e32 v134, v113, v134
	v_cvt_pk_bf16_f32 v104, v110, v111
	v_add_f32_e32 v251, v251, v134
	v_cvt_pk_bf16_f32 v105, v112, v113
	s_waitcnt lgkmcnt(4)
	v_mfma_f32_32x32x16_bf16 v[50:65], v[178:181], v[98:101], v[50:65]
	v_exp_f32_e32 v114, v114
	v_exp_f32_e32 v115, v115
	v_exp_f32_e32 v116, v116
	v_exp_f32_e32 v117, v117
	v_mfma_f32_32x32x16_bf16 v[34:49], v[182:185], v[98:101], v[34:49]
	v_add_f32_e32 v134, v115, v114
	v_exp_f32_e32 v118, v118
	v_add_f32_e32 v134, v116, v134
	v_exp_f32_e32 v119, v119
	v_mfma_f32_32x32x16_bf16 v[50:65], v[186:189], v[102:105], v[50:65]
	v_add_f32_e32 v134, v117, v134
	v_exp_f32_e32 v120, v120
	v_add_f32_e32 v134, v118, v134
	v_exp_f32_e32 v121, v121
	v_mfma_f32_32x32x16_bf16 v[34:49], v[190:193], v[102:105], v[34:49]
	v_add_f32_e32 v134, v119, v134
	v_cvt_pk_bf16_f32 v114, v114, v115
	v_exp_f32_e32 v122, v122
	v_add_f32_e32 v134, v120, v134
	s_waitcnt lgkmcnt(0)
	v_mfma_f32_32x32x16_bf16 v[98:113], v[194:197], v[154:157], 0
	v_cvt_pk_bf16_f32 v115, v116, v117
	v_exp_f32_e32 v123, v123
	v_add_f32_e32 v134, v121, v134
	v_cvt_pk_bf16_f32 v116, v118, v119
	v_mfma_f32_32x32x16_bf16 v[98:113], v[198:201], v[158:161], v[98:113]
	v_exp_f32_e32 v124, v124
	v_add_f32_e32 v134, v122, v134
	v_cvt_pk_bf16_f32 v117, v120, v121
	v_exp_f32_e32 v125, v125
	v_mfma_f32_32x32x16_bf16 v[98:113], v[202:205], v[146:149], v[98:113]
	v_add_f32_e32 v134, v123, v134
	v_exp_f32_e32 v126, v126
	v_add_f32_e32 v134, v124, v134
	v_exp_f32_e32 v127, v127
	v_mfma_f32_32x32x16_bf16 v[98:113], v[206:209], v[150:153], v[98:113]
	v_add_f32_e32 v134, v125, v134
	v_exp_f32_e32 v128, v128
	v_add_f32_e32 v134, v126, v134
	v_exp_f32_e32 v129, v129
	v_add_f32_e32 v134, v127, v134
	v_cvt_pk_bf16_f32 v118, v122, v123
	v_add_f32_e32 v134, v128, v134
	v_cvt_pk_bf16_f32 v119, v124, v125
	v_add_f32_e32 v134, v129, v134
	v_cvt_pk_bf16_f32 v120, v126, v127
	v_add_f32_e32 v250, v250, v134
	v_cvt_pk_bf16_f32 v121, v128, v129
	v_mfma_f32_32x32x16_bf16 v[18:33], v[178:181], v[114:117], v[18:33]
	v_exp_f32_e32 v98, v98
	v_exp_f32_e32 v99, v99
	v_exp_f32_e32 v100, v100
	v_exp_f32_e32 v101, v101
	v_mfma_f32_32x32x16_bf16 v[2:17], v[182:185], v[114:117], v[2:17]
	v_add_f32_e32 v134, v99, v98
	v_exp_f32_e32 v102, v102
	v_add_f32_e32 v134, v100, v134
	v_exp_f32_e32 v103, v103
	v_mfma_f32_32x32x16_bf16 v[18:33], v[186:189], v[118:121], v[18:33]
	v_add_f32_e32 v134, v101, v134
	v_exp_f32_e32 v104, v104
	v_add_f32_e32 v134, v102, v134
	v_exp_f32_e32 v105, v105
	v_mfma_f32_32x32x16_bf16 v[2:17], v[190:193], v[118:121], v[2:17]
	ds_read_b128 v[178:181], v132 offset:24576
	ds_read_b128 v[182:185], v132 offset:28672
	ds_read_b128 v[186:189], v133 offset:24576
	ds_read_b128 v[190:193], v133 offset:28672
	v_add_f32_e32 v134, v103, v134
	v_cvt_pk_bf16_f32 v98, v98, v99
	v_exp_f32_e32 v106, v106
	v_add_f32_e32 v134, v104, v134
	v_mfma_f32_32x32x16_bf16 v[114:129], v[194:197], v[162:165], 0
	v_cvt_pk_bf16_f32 v99, v100, v101
	v_exp_f32_e32 v107, v107
	v_add_f32_e32 v134, v105, v134
	v_cvt_pk_bf16_f32 v100, v102, v103
	v_mfma_f32_32x32x16_bf16 v[114:129], v[198:201], v[166:169], v[114:129]
	v_exp_f32_e32 v108, v108
	v_add_f32_e32 v134, v106, v134
	v_cvt_pk_bf16_f32 v101, v104, v105
	v_exp_f32_e32 v109, v109
	v_mfma_f32_32x32x16_bf16 v[114:129], v[202:205], v[170:173], v[114:129]
	v_add_f32_e32 v134, v107, v134
	v_exp_f32_e32 v110, v110
	v_add_f32_e32 v134, v108, v134
	v_exp_f32_e32 v111, v111
	v_mfma_f32_32x32x16_bf16 v[114:129], v[206:209], v[174:177], v[114:129]
	s_waitcnt vmcnt(0) lgkmcnt(0)
	s_barrier
	s_cmp_gt_u32 s28, 6
	s_cbranch_scc1 .La_nodma_6
	s_mov_b64 s[18:19], 0xa6000
	v_lshl_add_u64 v[216:217], v[216:217], 0, s[18:19]
	s_mov_b64 s[18:19], 0x100
	v_lshl_add_u64 v[214:215], v[214:215], 0, s[18:19]
	v_mov_b32_e32 v142, v243
	v_lshl_add_u64 v[136:137], v[216:217], 0, v[0:1]
	s_mov_b64 s[18:19], 0x44a6500
	v_readfirstlane_b32 s1, v142
	v_lshl_add_u64 v[138:139], v[136:137], 0, s[18:19]
	s_mov_b32 m0, s1
	v_add_u32_e32 v142, 0x2000, v142
	global_load_lds_dwordx4 v[138:139], off
	v_lshl_add_u64 v[138:139], v[214:215], 0, v[0:1]
	s_mov_b64 s[18:19], 0x11600100
	v_readfirstlane_b32 s1, v142
	v_lshl_add_u64 v[140:141], v[138:139], 0, s[18:19]
	s_mov_b32 m0, s1
	v_add_u32_e32 v142, 0x4000, v243
	global_load_lds_dwordx4 v[140:141], off
	s_mov_b64 s[18:19], 0x44f9500
	v_readfirstlane_b32 s1, v142
	v_lshl_add_u64 v[136:137], v[136:137], 0, s[18:19]
	s_mov_b32 m0, s1
	s_mov_b64 s[18:19], 0x11600180
	global_load_lds_dwordx4 v[136:137], off
	v_lshl_add_u64 v[136:137], v[138:139], 0, s[18:19]
	v_add_u32_e32 v142, 0x2000, v142
	s_nop 0
	v_readfirstlane_b32 s1, v142
	s_mov_b32 m0, s1
	s_nop 0
	global_load_lds_dwordx4 v[136:137], off
.La_nodma_6:
	ds_read_b128 v[194:197], v213 offset:32768
	ds_read_b128 v[198:201], v240 offset:32768
	ds_read_b128 v[202:205], v241 offset:32768
	ds_read_b128 v[206:209], v242 offset:32768
	v_add_f32_e32 v134, v109, v134
	v_exp_f32_e32 v112, v112
	v_add_f32_e32 v134, v110, v134
	v_exp_f32_e32 v113, v113
	v_add_f32_e32 v134, v111, v134
	v_cvt_pk_bf16_f32 v102, v106, v107
	v_add_f32_e32 v134, v112, v134
	v_cvt_pk_bf16_f32 v103, v108, v109
	v_add_f32_e32 v134, v113, v134
	v_cvt_pk_bf16_f32 v104, v110, v111
	v_add_f32_e32 v251, v251, v134
	v_cvt_pk_bf16_f32 v105, v112, v113
	s_waitcnt lgkmcnt(4)
	v_mfma_f32_32x32x16_bf16 v[50:65], v[178:181], v[98:101], v[50:65]
	v_exp_f32_e32 v114, v114
	v_exp_f32_e32 v115, v115
	v_exp_f32_e32 v116, v116
	v_exp_f32_e32 v117, v117
	v_mfma_f32_32x32x16_bf16 v[34:49], v[182:185], v[98:101], v[34:49]
	v_add_f32_e32 v134, v115, v114
	v_exp_f32_e32 v118, v118
	v_add_f32_e32 v134, v116, v134
	v_exp_f32_e32 v119, v119
	v_mfma_f32_32x32x16_bf16 v[50:65], v[186:189], v[102:105], v[50:65]
	v_add_f32_e32 v134, v117, v134
	v_exp_f32_e32 v120, v120
	v_add_f32_e32 v134, v118, v134
	v_exp_f32_e32 v121, v121
	v_mfma_f32_32x32x16_bf16 v[34:49], v[190:193], v[102:105], v[34:49]
	v_add_f32_e32 v134, v119, v134
	v_cvt_pk_bf16_f32 v114, v114, v115
	v_exp_f32_e32 v122, v122
	v_add_f32_e32 v134, v120, v134
	s_waitcnt lgkmcnt(0)
	v_mfma_f32_32x32x16_bf16 v[98:113], v[194:197], v[154:157], 0
	v_cvt_pk_bf16_f32 v115, v116, v117
	v_exp_f32_e32 v123, v123
	v_add_f32_e32 v134, v121, v134
	v_cvt_pk_bf16_f32 v116, v118, v119
	v_mfma_f32_32x32x16_bf16 v[98:113], v[198:201], v[158:161], v[98:113]
	v_exp_f32_e32 v124, v124
	v_add_f32_e32 v134, v122, v134
	v_cvt_pk_bf16_f32 v117, v120, v121
	v_exp_f32_e32 v125, v125
	v_mfma_f32_32x32x16_bf16 v[98:113], v[202:205], v[146:149], v[98:113]
	v_add_f32_e32 v134, v123, v134
	v_exp_f32_e32 v126, v126
	v_add_f32_e32 v134, v124, v134
	v_exp_f32_e32 v127, v127
	v_mfma_f32_32x32x16_bf16 v[98:113], v[206:209], v[150:153], v[98:113]
	v_add_f32_e32 v134, v125, v134
	v_exp_f32_e32 v128, v128
	v_add_f32_e32 v134, v126, v134
	v_exp_f32_e32 v129, v129
	v_add_f32_e32 v134, v127, v134
	v_cvt_pk_bf16_f32 v118, v122, v123
	v_add_f32_e32 v134, v128, v134
	v_cvt_pk_bf16_f32 v119, v124, v125
	v_add_f32_e32 v134, v129, v134
	v_cvt_pk_bf16_f32 v120, v126, v127
	v_add_f32_e32 v250, v250, v134
	v_cvt_pk_bf16_f32 v121, v128, v129
	v_mfma_f32_32x32x16_bf16 v[18:33], v[178:181], v[114:117], v[18:33]
	v_exp_f32_e32 v98, v98
	v_exp_f32_e32 v99, v99
	v_exp_f32_e32 v100, v100
	v_exp_f32_e32 v101, v101
	v_mfma_f32_32x32x16_bf16 v[2:17], v[182:185], v[114:117], v[2:17]
	v_add_f32_e32 v134, v99, v98
	v_exp_f32_e32 v102, v102
	v_add_f32_e32 v134, v100, v134
	v_exp_f32_e32 v103, v103
	v_mfma_f32_32x32x16_bf16 v[18:33], v[186:189], v[118:121], v[18:33]
	v_add_f32_e32 v134, v101, v134
	v_exp_f32_e32 v104, v104
	v_add_f32_e32 v134, v102, v134
	v_exp_f32_e32 v105, v105
	v_mfma_f32_32x32x16_bf16 v[2:17], v[190:193], v[118:121], v[2:17]
	ds_read_b128 v[178:181], v130 offset:40960
	ds_read_b128 v[182:185], v130 offset:45056
	ds_read_b128 v[186:189], v131 offset:40960
	ds_read_b128 v[190:193], v131 offset:45056
	v_add_f32_e32 v134, v103, v134
	v_cvt_pk_bf16_f32 v98, v98, v99
	v_exp_f32_e32 v106, v106
	v_add_f32_e32 v134, v104, v134
	v_mfma_f32_32x32x16_bf16 v[114:129], v[194:197], v[162:165], 0
	v_cvt_pk_bf16_f32 v99, v100, v101
	v_exp_f32_e32 v107, v107
	v_add_f32_e32 v134, v105, v134
	v_cvt_pk_bf16_f32 v100, v102, v103
	v_mfma_f32_32x32x16_bf16 v[114:129], v[198:201], v[166:169], v[114:129]
	v_exp_f32_e32 v108, v108
	v_add_f32_e32 v134, v106, v134
	v_cvt_pk_bf16_f32 v101, v104, v105
	v_exp_f32_e32 v109, v109
	v_mfma_f32_32x32x16_bf16 v[114:129], v[202:205], v[170:173], v[114:129]
	v_add_f32_e32 v134, v107, v134
	v_exp_f32_e32 v110, v110
	v_add_f32_e32 v134, v108, v134
	v_exp_f32_e32 v111, v111
	v_mfma_f32_32x32x16_bf16 v[114:129], v[206:209], v[174:177], v[114:129]
	ds_read_b128 v[194:197], v213 offset:36864
	ds_read_b128 v[198:201], v240 offset:36864
	ds_read_b128 v[202:205], v241 offset:36864
	ds_read_b128 v[206:209], v242 offset:36864
	v_add_f32_e32 v134, v109, v134
	v_exp_f32_e32 v112, v112
	v_add_f32_e32 v134, v110, v134
	v_exp_f32_e32 v113, v113
	v_add_f32_e32 v134, v111, v134
	v_cvt_pk_bf16_f32 v102, v106, v107
	v_add_f32_e32 v134, v112, v134
	v_cvt_pk_bf16_f32 v103, v108, v109
	v_add_f32_e32 v134, v113, v134
	v_cvt_pk_bf16_f32 v104, v110, v111
	v_add_f32_e32 v251, v251, v134
	v_cvt_pk_bf16_f32 v105, v112, v113
	s_waitcnt lgkmcnt(4)
	v_mfma_f32_32x32x16_bf16 v[50:65], v[178:181], v[98:101], v[50:65]
	v_exp_f32_e32 v114, v114
	v_exp_f32_e32 v115, v115
	v_exp_f32_e32 v116, v116
	v_exp_f32_e32 v117, v117
	v_mfma_f32_32x32x16_bf16 v[34:49], v[182:185], v[98:101], v[34:49]
	v_add_f32_e32 v134, v115, v114
	v_exp_f32_e32 v118, v118
	v_add_f32_e32 v134, v116, v134
	v_exp_f32_e32 v119, v119
	v_mfma_f32_32x32x16_bf16 v[50:65], v[186:189], v[102:105], v[50:65]
	v_add_f32_e32 v134, v117, v134
	v_exp_f32_e32 v120, v120
	v_add_f32_e32 v134, v118, v134
	v_exp_f32_e32 v121, v121
	v_mfma_f32_32x32x16_bf16 v[34:49], v[190:193], v[102:105], v[34:49]
	v_add_f32_e32 v134, v119, v134
	v_cvt_pk_bf16_f32 v114, v114, v115
	v_exp_f32_e32 v122, v122
	v_add_f32_e32 v134, v120, v134
	s_waitcnt lgkmcnt(0)
	v_mfma_f32_32x32x16_bf16 v[98:113], v[194:197], v[154:157], 0
	v_cvt_pk_bf16_f32 v115, v116, v117
	v_exp_f32_e32 v123, v123
	v_add_f32_e32 v134, v121, v134
	v_cvt_pk_bf16_f32 v116, v118, v119
	v_mfma_f32_32x32x16_bf16 v[98:113], v[198:201], v[158:161], v[98:113]
	v_exp_f32_e32 v124, v124
	v_add_f32_e32 v134, v122, v134
	v_cvt_pk_bf16_f32 v117, v120, v121
	v_exp_f32_e32 v125, v125
	v_mfma_f32_32x32x16_bf16 v[98:113], v[202:205], v[146:149], v[98:113]
	v_add_f32_e32 v134, v123, v134
	v_exp_f32_e32 v126, v126
	v_add_f32_e32 v134, v124, v134
	v_exp_f32_e32 v127, v127
	v_mfma_f32_32x32x16_bf16 v[98:113], v[206:209], v[150:153], v[98:113]
	v_add_f32_e32 v134, v125, v134
	v_exp_f32_e32 v128, v128
	v_add_f32_e32 v134, v126, v134
	v_exp_f32_e32 v129, v129
	v_add_f32_e32 v134, v127, v134
	v_cvt_pk_bf16_f32 v118, v122, v123
	v_add_f32_e32 v134, v128, v134
	v_cvt_pk_bf16_f32 v119, v124, v125
	v_add_f32_e32 v134, v129, v134
	v_cvt_pk_bf16_f32 v120, v126, v127
	v_add_f32_e32 v250, v250, v134
	v_cvt_pk_bf16_f32 v121, v128, v129
	v_mfma_f32_32x32x16_bf16 v[18:33], v[178:181], v[114:117], v[18:33]
	v_exp_f32_e32 v98, v98
	v_exp_f32_e32 v99, v99
	v_exp_f32_e32 v100, v100
	v_exp_f32_e32 v101, v101
	v_mfma_f32_32x32x16_bf16 v[2:17], v[182:185], v[114:117], v[2:17]
	v_add_f32_e32 v134, v99, v98
	v_exp_f32_e32 v102, v102
	v_add_f32_e32 v134, v100, v134
	v_exp_f32_e32 v103, v103
	v_mfma_f32_32x32x16_bf16 v[18:33], v[186:189], v[118:121], v[18:33]
	v_add_f32_e32 v134, v101, v134
	v_exp_f32_e32 v104, v104
	v_add_f32_e32 v134, v102, v134
	v_exp_f32_e32 v105, v105
	v_mfma_f32_32x32x16_bf16 v[2:17], v[190:193], v[118:121], v[2:17]
	ds_read_b128 v[178:181], v132 offset:40960
	ds_read_b128 v[182:185], v132 offset:45056
	ds_read_b128 v[186:189], v133 offset:40960
	ds_read_b128 v[190:193], v133 offset:45056
	v_add_f32_e32 v134, v103, v134
	v_cvt_pk_bf16_f32 v98, v98, v99
	v_exp_f32_e32 v106, v106
	v_add_f32_e32 v134, v104, v134
	v_mfma_f32_32x32x16_bf16 v[114:129], v[194:197], v[162:165], 0
	v_cvt_pk_bf16_f32 v99, v100, v101
	v_exp_f32_e32 v107, v107
	v_add_f32_e32 v134, v105, v134
	v_cvt_pk_bf16_f32 v100, v102, v103
	v_mfma_f32_32x32x16_bf16 v[114:129], v[198:201], v[166:169], v[114:129]
	v_exp_f32_e32 v108, v108
	v_add_f32_e32 v134, v106, v134
	v_cvt_pk_bf16_f32 v101, v104, v105
	v_exp_f32_e32 v109, v109
	v_mfma_f32_32x32x16_bf16 v[114:129], v[202:205], v[170:173], v[114:129]
	v_add_f32_e32 v134, v107, v134
	v_exp_f32_e32 v110, v110
	v_add_f32_e32 v134, v108, v134
	v_exp_f32_e32 v111, v111
	v_mfma_f32_32x32x16_bf16 v[114:129], v[206:209], v[174:177], v[114:129]
	ds_read_b128 v[194:197], v213 offset:49152
	ds_read_b128 v[198:201], v240 offset:49152
	ds_read_b128 v[202:205], v241 offset:49152
	ds_read_b128 v[206:209], v242 offset:49152
	v_add_f32_e32 v134, v109, v134
	v_exp_f32_e32 v112, v112
	v_add_f32_e32 v134, v110, v134
	v_exp_f32_e32 v113, v113
	v_add_f32_e32 v134, v111, v134
	v_cvt_pk_bf16_f32 v102, v106, v107
	v_add_f32_e32 v134, v112, v134
	v_cvt_pk_bf16_f32 v103, v108, v109
	v_add_f32_e32 v134, v113, v134
	v_cvt_pk_bf16_f32 v104, v110, v111
	v_add_f32_e32 v251, v251, v134
	v_cvt_pk_bf16_f32 v105, v112, v113
	s_waitcnt lgkmcnt(4)
	v_mfma_f32_32x32x16_bf16 v[50:65], v[178:181], v[98:101], v[50:65]
	v_exp_f32_e32 v114, v114
	v_exp_f32_e32 v115, v115
	v_exp_f32_e32 v116, v116
	v_exp_f32_e32 v117, v117
	v_mfma_f32_32x32x16_bf16 v[34:49], v[182:185], v[98:101], v[34:49]
	v_add_f32_e32 v134, v115, v114
	v_exp_f32_e32 v118, v118
	v_add_f32_e32 v134, v116, v134
	v_exp_f32_e32 v119, v119
	v_mfma_f32_32x32x16_bf16 v[50:65], v[186:189], v[102:105], v[50:65]
	v_add_f32_e32 v134, v117, v134
	v_exp_f32_e32 v120, v120
	v_add_f32_e32 v134, v118, v134
	v_exp_f32_e32 v121, v121
	v_mfma_f32_32x32x16_bf16 v[34:49], v[190:193], v[102:105], v[34:49]
	v_add_f32_e32 v134, v119, v134
	v_cvt_pk_bf16_f32 v114, v114, v115
	v_exp_f32_e32 v122, v122
	v_add_f32_e32 v134, v120, v134
	s_waitcnt lgkmcnt(0)
	v_mfma_f32_32x32x16_bf16 v[98:113], v[194:197], v[154:157], 0
	v_cvt_pk_bf16_f32 v115, v116, v117
	v_exp_f32_e32 v123, v123
	v_add_f32_e32 v134, v121, v134
	v_cvt_pk_bf16_f32 v116, v118, v119
	v_mfma_f32_32x32x16_bf16 v[98:113], v[198:201], v[158:161], v[98:113]
	v_exp_f32_e32 v124, v124
	v_add_f32_e32 v134, v122, v134
	v_cvt_pk_bf16_f32 v117, v120, v121
	v_exp_f32_e32 v125, v125
	v_mfma_f32_32x32x16_bf16 v[98:113], v[202:205], v[146:149], v[98:113]
	v_add_f32_e32 v134, v123, v134
	v_exp_f32_e32 v126, v126
	v_add_f32_e32 v134, v124, v134
	v_exp_f32_e32 v127, v127
	v_mfma_f32_32x32x16_bf16 v[98:113], v[206:209], v[150:153], v[98:113]
	v_add_f32_e32 v134, v125, v134
	v_exp_f32_e32 v128, v128
	v_add_f32_e32 v134, v126, v134
	v_exp_f32_e32 v129, v129
	v_add_f32_e32 v134, v127, v134
	v_cvt_pk_bf16_f32 v118, v122, v123
	v_add_f32_e32 v134, v128, v134
	v_cvt_pk_bf16_f32 v119, v124, v125
	v_add_f32_e32 v134, v129, v134
	v_cvt_pk_bf16_f32 v120, v126, v127
	v_add_f32_e32 v250, v250, v134
	v_cvt_pk_bf16_f32 v121, v128, v129
	v_mfma_f32_32x32x16_bf16 v[18:33], v[178:181], v[114:117], v[18:33]
	v_exp_f32_e32 v98, v98
	v_exp_f32_e32 v99, v99
	v_exp_f32_e32 v100, v100
	v_exp_f32_e32 v101, v101
	v_mfma_f32_32x32x16_bf16 v[2:17], v[182:185], v[114:117], v[2:17]
	v_add_f32_e32 v134, v99, v98
	v_exp_f32_e32 v102, v102
	v_add_f32_e32 v134, v100, v134
	v_exp_f32_e32 v103, v103
	v_mfma_f32_32x32x16_bf16 v[18:33], v[186:189], v[118:121], v[18:33]
	v_add_f32_e32 v134, v101, v134
	v_exp_f32_e32 v104, v104
	v_add_f32_e32 v134, v102, v134
	v_exp_f32_e32 v105, v105
	v_mfma_f32_32x32x16_bf16 v[2:17], v[190:193], v[118:121], v[2:17]
	ds_read_b128 v[178:181], v130 offset:57344
	ds_read_b128 v[182:185], v130 offset:61440
	ds_read_b128 v[186:189], v131 offset:57344
	ds_read_b128 v[190:193], v131 offset:61440
	v_add_f32_e32 v134, v103, v134
	v_cvt_pk_bf16_f32 v98, v98, v99
	v_exp_f32_e32 v106, v106
	v_add_f32_e32 v134, v104, v134
	v_mfma_f32_32x32x16_bf16 v[114:129], v[194:197], v[162:165], 0
	v_cvt_pk_bf16_f32 v99, v100, v101
	v_exp_f32_e32 v107, v107
	v_add_f32_e32 v134, v105, v134
	v_cvt_pk_bf16_f32 v100, v102, v103
	v_mfma_f32_32x32x16_bf16 v[114:129], v[198:201], v[166:169], v[114:129]
	v_exp_f32_e32 v108, v108
	v_add_f32_e32 v134, v106, v134
	v_cvt_pk_bf16_f32 v101, v104, v105
	v_exp_f32_e32 v109, v109
	v_mfma_f32_32x32x16_bf16 v[114:129], v[202:205], v[170:173], v[114:129]
	v_add_f32_e32 v134, v107, v134
	v_exp_f32_e32 v110, v110
	v_add_f32_e32 v134, v108, v134
	v_exp_f32_e32 v111, v111
	v_mfma_f32_32x32x16_bf16 v[114:129], v[206:209], v[174:177], v[114:129]
	ds_read_b128 v[194:197], v213 offset:53248
	ds_read_b128 v[198:201], v240 offset:53248
	ds_read_b128 v[202:205], v241 offset:53248
	ds_read_b128 v[206:209], v242 offset:53248
	v_add_f32_e32 v134, v109, v134
	v_exp_f32_e32 v112, v112
	v_add_f32_e32 v134, v110, v134
	v_exp_f32_e32 v113, v113
	v_add_f32_e32 v134, v111, v134
	v_cvt_pk_bf16_f32 v102, v106, v107
	v_add_f32_e32 v134, v112, v134
	v_cvt_pk_bf16_f32 v103, v108, v109
	v_add_f32_e32 v134, v113, v134
	v_cvt_pk_bf16_f32 v104, v110, v111
	v_add_f32_e32 v251, v251, v134
	v_cvt_pk_bf16_f32 v105, v112, v113
	s_waitcnt lgkmcnt(4)
	v_mfma_f32_32x32x16_bf16 v[50:65], v[178:181], v[98:101], v[50:65]
	v_exp_f32_e32 v114, v114
	v_exp_f32_e32 v115, v115
	v_exp_f32_e32 v116, v116
	v_exp_f32_e32 v117, v117
	v_mfma_f32_32x32x16_bf16 v[34:49], v[182:185], v[98:101], v[34:49]
	v_add_f32_e32 v134, v115, v114
	v_exp_f32_e32 v118, v118
	v_add_f32_e32 v134, v116, v134
	v_exp_f32_e32 v119, v119
	v_mfma_f32_32x32x16_bf16 v[50:65], v[186:189], v[102:105], v[50:65]
	v_add_f32_e32 v134, v117, v134
	v_exp_f32_e32 v120, v120
	v_add_f32_e32 v134, v118, v134
	v_exp_f32_e32 v121, v121
	v_mfma_f32_32x32x16_bf16 v[34:49], v[190:193], v[102:105], v[34:49]
	v_add_f32_e32 v134, v119, v134
	v_cvt_pk_bf16_f32 v114, v114, v115
	v_exp_f32_e32 v122, v122
	v_add_f32_e32 v134, v120, v134
	s_waitcnt lgkmcnt(0)
	v_mfma_f32_32x32x16_bf16 v[98:113], v[194:197], v[154:157], 0
	v_cvt_pk_bf16_f32 v115, v116, v117
	v_exp_f32_e32 v123, v123
	v_add_f32_e32 v134, v121, v134
	v_cvt_pk_bf16_f32 v116, v118, v119
	v_mfma_f32_32x32x16_bf16 v[98:113], v[198:201], v[158:161], v[98:113]
	v_exp_f32_e32 v124, v124
	v_add_f32_e32 v134, v122, v134
	v_cvt_pk_bf16_f32 v117, v120, v121
	v_exp_f32_e32 v125, v125
	v_mfma_f32_32x32x16_bf16 v[98:113], v[202:205], v[146:149], v[98:113]
	v_add_f32_e32 v134, v123, v134
	v_exp_f32_e32 v126, v126
	v_add_f32_e32 v134, v124, v134
	v_exp_f32_e32 v127, v127
	v_mfma_f32_32x32x16_bf16 v[98:113], v[206:209], v[150:153], v[98:113]
	v_add_f32_e32 v134, v125, v134
	v_exp_f32_e32 v128, v128
	v_add_f32_e32 v134, v126, v134
	v_exp_f32_e32 v129, v129
	v_add_f32_e32 v134, v127, v134
	v_cvt_pk_bf16_f32 v118, v122, v123
	v_add_f32_e32 v134, v128, v134
	v_cvt_pk_bf16_f32 v119, v124, v125
	v_add_f32_e32 v134, v129, v134
	v_cvt_pk_bf16_f32 v120, v126, v127
	v_add_f32_e32 v250, v250, v134
	v_cvt_pk_bf16_f32 v121, v128, v129
	v_mfma_f32_32x32x16_bf16 v[18:33], v[178:181], v[114:117], v[18:33]
	v_exp_f32_e32 v98, v98
	v_exp_f32_e32 v99, v99
	v_exp_f32_e32 v100, v100
	v_exp_f32_e32 v101, v101
	v_mfma_f32_32x32x16_bf16 v[2:17], v[182:185], v[114:117], v[2:17]
	v_add_f32_e32 v134, v99, v98
	v_exp_f32_e32 v102, v102
	v_add_f32_e32 v134, v100, v134
	v_exp_f32_e32 v103, v103
	v_mfma_f32_32x32x16_bf16 v[18:33], v[186:189], v[118:121], v[18:33]
	v_add_f32_e32 v134, v101, v134
	v_exp_f32_e32 v104, v104
	v_add_f32_e32 v134, v102, v134
	v_exp_f32_e32 v105, v105
	v_mfma_f32_32x32x16_bf16 v[2:17], v[190:193], v[118:121], v[2:17]
	ds_read_b128 v[178:181], v132 offset:57344
	ds_read_b128 v[182:185], v132 offset:61440
	ds_read_b128 v[186:189], v133 offset:57344
	ds_read_b128 v[190:193], v133 offset:61440
	v_add_f32_e32 v134, v103, v134
	v_cvt_pk_bf16_f32 v98, v98, v99
	v_exp_f32_e32 v106, v106
	v_add_f32_e32 v134, v104, v134
	v_mfma_f32_32x32x16_bf16 v[114:129], v[194:197], v[162:165], 0
	v_cvt_pk_bf16_f32 v99, v100, v101
	v_exp_f32_e32 v107, v107
	v_add_f32_e32 v134, v105, v134
	v_cvt_pk_bf16_f32 v100, v102, v103
	v_mfma_f32_32x32x16_bf16 v[114:129], v[198:201], v[166:169], v[114:129]
	v_exp_f32_e32 v108, v108
	v_add_f32_e32 v134, v106, v134
	v_cvt_pk_bf16_f32 v101, v104, v105
	v_exp_f32_e32 v109, v109
	v_mfma_f32_32x32x16_bf16 v[114:129], v[202:205], v[170:173], v[114:129]
	v_add_f32_e32 v134, v107, v134
	v_exp_f32_e32 v110, v110
	v_add_f32_e32 v134, v108, v134
	v_exp_f32_e32 v111, v111
	v_mfma_f32_32x32x16_bf16 v[114:129], v[206:209], v[174:177], v[114:129]
	s_waitcnt vmcnt(0) lgkmcnt(0)
	s_barrier
	s_cmp_gt_u32 s28, 6
	s_cbranch_scc1 .La_nodma_14
	s_mov_b64 s[18:19], 0xa6000
	v_lshl_add_u64 v[216:217], v[216:217], 0, s[18:19]
	s_mov_b64 s[18:19], 0x100
	v_lshl_add_u64 v[214:215], v[214:215], 0, s[18:19]
	v_add_u32_e32 v142, 0x8000, v243
	v_lshl_add_u64 v[136:137], v[216:217], 0, v[0:1]
	s_mov_b64 s[18:19], 0x44a6500
	v_readfirstlane_b32 s1, v142
	v_lshl_add_u64 v[138:139], v[136:137], 0, s[18:19]
	s_mov_b32 m0, s1
	v_add_u32_e32 v142, 0x2000, v142
	global_load_lds_dwordx4 v[138:139], off
	v_lshl_add_u64 v[138:139], v[214:215], 0, v[0:1]
	s_mov_b64 s[18:19], 0x11600100
	v_readfirstlane_b32 s1, v142
	v_lshl_add_u64 v[140:141], v[138:139], 0, s[18:19]
	s_mov_b32 m0, s1
	v_add_u32_e32 v142, 0xc000, v243
	global_load_lds_dwordx4 v[140:141], off
	s_mov_b64 s[18:19], 0x44f9500
	v_readfirstlane_b32 s1, v142
	v_lshl_add_u64 v[136:137], v[136:137], 0, s[18:19]
	s_mov_b32 m0, s1
	s_mov_b64 s[18:19], 0x11600180
	global_load_lds_dwordx4 v[136:137], off
	v_lshl_add_u64 v[136:137], v[138:139], 0, s[18:19]
	v_add_u32_e32 v142, 0x2000, v142
	s_nop 0
	v_readfirstlane_b32 s1, v142
	s_mov_b32 m0, s1
	s_nop 0
	global_load_lds_dwordx4 v[136:137], off
.La_nodma_14:
	ds_read_b128 v[194:197], v213
	ds_read_b128 v[198:201], v240
	ds_read_b128 v[202:205], v241
	ds_read_b128 v[206:209], v242
	v_add_f32_e32 v134, v109, v134
	v_exp_f32_e32 v112, v112
	v_add_f32_e32 v134, v110, v134
	v_exp_f32_e32 v113, v113
	v_add_f32_e32 v134, v111, v134
	v_cvt_pk_bf16_f32 v102, v106, v107
	v_add_f32_e32 v134, v112, v134
	v_cvt_pk_bf16_f32 v103, v108, v109
	v_add_f32_e32 v134, v113, v134
	v_cvt_pk_bf16_f32 v104, v110, v111
	v_add_f32_e32 v251, v251, v134
	v_cvt_pk_bf16_f32 v105, v112, v113
	s_waitcnt lgkmcnt(4)
	v_mfma_f32_32x32x16_bf16 v[50:65], v[178:181], v[98:101], v[50:65]
	v_exp_f32_e32 v114, v114
	v_exp_f32_e32 v115, v115
	v_exp_f32_e32 v116, v116
	v_exp_f32_e32 v117, v117
	v_mfma_f32_32x32x16_bf16 v[34:49], v[182:185], v[98:101], v[34:49]
	v_add_f32_e32 v134, v115, v114
	v_exp_f32_e32 v118, v118
	v_add_f32_e32 v134, v116, v134
	v_exp_f32_e32 v119, v119
	v_mfma_f32_32x32x16_bf16 v[50:65], v[186:189], v[102:105], v[50:65]
	v_add_f32_e32 v134, v117, v134
	v_exp_f32_e32 v120, v120
	v_add_f32_e32 v134, v118, v134
	v_exp_f32_e32 v121, v121
	v_mfma_f32_32x32x16_bf16 v[34:49], v[190:193], v[102:105], v[34:49]
	v_add_f32_e32 v134, v119, v134
	v_cvt_pk_bf16_f32 v114, v114, v115
	v_exp_f32_e32 v122, v122
	v_add_f32_e32 v134, v120, v134
	s_waitcnt lgkmcnt(0)
	v_mfma_f32_32x32x16_bf16 v[98:113], v[194:197], v[154:157], 0
	v_cvt_pk_bf16_f32 v115, v116, v117
	v_exp_f32_e32 v123, v123
	v_add_f32_e32 v134, v121, v134
	v_cvt_pk_bf16_f32 v116, v118, v119
	v_mfma_f32_32x32x16_bf16 v[98:113], v[198:201], v[158:161], v[98:113]
	v_exp_f32_e32 v124, v124
	v_add_f32_e32 v134, v122, v134
	v_cvt_pk_bf16_f32 v117, v120, v121
	v_exp_f32_e32 v125, v125
	v_mfma_f32_32x32x16_bf16 v[98:113], v[202:205], v[146:149], v[98:113]
	v_add_f32_e32 v134, v123, v134
	v_exp_f32_e32 v126, v126
	v_add_f32_e32 v134, v124, v134
	v_exp_f32_e32 v127, v127
	v_mfma_f32_32x32x16_bf16 v[98:113], v[206:209], v[150:153], v[98:113]
	v_add_f32_e32 v134, v125, v134
	v_exp_f32_e32 v128, v128
	v_add_f32_e32 v134, v126, v134
	v_exp_f32_e32 v129, v129
	v_add_f32_e32 v134, v127, v134
	v_cvt_pk_bf16_f32 v118, v122, v123
	v_add_f32_e32 v134, v128, v134
	v_cvt_pk_bf16_f32 v119, v124, v125
	v_add_f32_e32 v134, v129, v134
	v_cvt_pk_bf16_f32 v120, v126, v127
	v_add_f32_e32 v250, v250, v134
	v_cvt_pk_bf16_f32 v121, v128, v129
	s_add_i32 s28, s28, 1
	s_cmp_lg_u32 s28, 8
	s_cbranch_scc1 .La_loop
	v_mfma_f32_32x32x16_bf16 v[18:33], v[178:181], v[114:117], v[18:33]
	v_mfma_f32_32x32x16_bf16 v[2:17], v[182:185], v[114:117], v[2:17]
	v_mfma_f32_32x32x16_bf16 v[18:33], v[186:189], v[118:121], v[18:33]
	v_mfma_f32_32x32x16_bf16 v[2:17], v[190:193], v[118:121], v[2:17]
	s_nop 15
